# v47 + rw_post loads staged through LDS (WG-cooperative 1-2KB row segments)
# speedup vs baseline: 1.0069x; 1.0023x over previous
; #define POST_LD(Y_, V_, G_, R_, C_, t) do { _Pragma("unroll") for (int q = 0; q < 8; ++q) { const size_t o_ = (size_t)((t) + q) * DH; Y_[q] = yp[o_]; V_[q] = vp[o_]; G_[q] = gp[o_]; R_[q] = rp[((t) + q) * 32]; C_[q] = cp[o_]; } } while (0)
; __device__ __forceinline__ void rw_post(Frame& F) {
;     const float* Y = (const float*)(F.ws + WS_Y); const float* C = (const float*)(F.ws + WS_C); const float* SST = (const float*)(F.ws + WS_SST); const float* VS = (const float*)(F.ws + WS_VS);
;     const float* RK = (const float*)(F.ws + WS_RK); const bf16* G = (const bf16*)(F.ws + WS_G);
;     bf16* OB = (bf16*)(F.ws + WS_OB); const float* lng = F.in[I_LNG]; const float* lnb = F.in[I_LNB];
;     const int lane = F.lane;
;     for (int u = F.gw; u < 32 * (MR / 64); u += F.NGW) { const int h = u & 31, rb0 = (u >> 5) * 64, col = h * 64 + lane;
;         const float g_ = lng[col], b_ = lnb[col];
;         const int k = rb0 < MPR ? (rb0 / SEGLEN) : 0;
;         f32x4 Sr[16];
;         if (k > 0) {
; #pragma unroll
;             for (int q = 0; q < 16; ++q) Sr[q] = *(const f32x4*)(SST + ((size_t)(h * NSEG + k) * 64 + lane) * 64 + 4 * q); }
;         const float* yp = Y + (size_t)rb0 * DH + col; const float* vp = VS + (size_t)rb0 * DH + col; const bf16* gp = G + (size_t)rb0 * DH + col; const float* rp = RK + (size_t)rb0 * 32 + h;
;         const float* cp = k > 0 ? C + (size_t)(rb0 - SEGLEN) * DH + col : yp;
;         float y[8], vv[8], rk[8], cc[8]; bf16 gg[8];
;     ...
;         POST_LD(y, vv, gg, rk, cc, 0);
.LBB0_1160:
	s_or_b64 exec, exec, s[6:7]
	s_cmpk_gt_i32 s94, 0x203f
	s_waitcnt lgkmcnt(0)
	s_barrier
	s_cbranch_scc1 .LBB0_1170
	s_load_dwordx4 s[16:19], s[74:75], 0xc0
	v_readlane_b32 s24, v240, 2
	v_lshlrev_b32_e32 v1, 2, v178
	v_lshlrev_b32_e32 v2, 1, v178
	v_lshlrev_b32_e32 v10, 8, v178
	v_lshlrev_b32_e32 v11, 4, v178
	v_mov_b32_e32 v5, 0
	v_mov_b32_e32 v8, 0x260
	v_mov_b32_e32 v9, 0x3a27c5ac
	s_mov_b32 s68, 0xf800000
	s_mov_b32 s33, s24
	s_lshl_b32 s30, s24, 11
	v_add_u32_e32 v12, s30, v11
	v_add_u32_e32 v13, 0xe000, v12
	s_lshl_b32 s30, s24, 10
	s_add_i32 s30, s30, 0xc000
	v_add_u32_e32 v14, s30, v11
	v_add_u32_e32 v15, 0xe000, v14
	s_lshl_b32 s30, s24, 8
	v_add_u32_e32 v149, s30, v1
	v_add_u32_e32 v150, 0xe000, v149
	s_lshl_b32 s30, s24, 7
	s_add_i32 s30, s30, 0xc000
	v_add_u32_e32 v151, s30, v2
	v_add_u32_e32 v152, 0xe000, v151
	v_and_b32_e32 v153, 7, v178
	v_lshlrev_b32_e32 v153, 7, v153
	s_lshl_b32 s24, s24, 10
	s_add_i32 s24, s24, 0x20000
	v_mov_b32_e32 v4, s24
	v_add_u32_e32 v3, s24, v1
	s_mov_b32 s20, s94
	s_waitcnt lgkmcnt(0)
.Lpo_unit:
	s_and_b32 s21, s20, 31
	s_lshr_b32 s22, s20, 5
	s_lshl_b32 s22, s22, 6
	s_lshr_b32 s23, s22, 10
	s_cmpk_lt_i32 s22, 0x4000
	s_cselect_b32 s23, s23, 0
	s_add_i32 s34, s22, s33
	s_and_b32 s35, s21, 24
	s_lshl_b32 s30, s34, 13
	s_lshl_b32 s31, s35, 8
	s_add_u32 s30, s30, s31
	s_add_u32 s6, s90, s30
	s_addc_u32 s7, s91, 0
	s_add_u32 s8, s6, 0x28700000
	s_addc_u32 s9, s7, 0
	s_add_u32 s14, s6, 0x39900000
	s_addc_u32 s15, s7, 0
	s_add_u32 s30, s6, 0x41200000
	s_addc_u32 s31, s7, 0
	s_add_u32 s6, s6, 0x39900000
	s_addc_u32 s7, s7, 0
	s_cmp_eq_u32 s23, 0
	s_cselect_b32 s14, s14, s30
	s_cselect_b32 s15, s15, s31
	s_lshl_b32 s30, s34, 12
	s_lshl_b32 s31, s35, 7
	s_add_u32 s30, s30, s31
	s_add_u32 s10, s90, s30
	s_addc_u32 s11, s91, 0
	s_add_u32 s10, s10, 0x30800000
	s_addc_u32 s11, s11, 0
	s_lshl_b32 s30, s22, 12
	s_lshl_b32 s31, s21, 7
	s_add_u32 s30, s30, s31
	s_add_u32 s28, s90, s30
	s_addc_u32 s29, s91, 0
	s_add_u32 s28, s28, 0x18500000
	s_addc_u32 s29, s29, 0
	s_lshl_b32 s30, s22, 7
	s_lshl_b32 s31, s21, 2
	s_add_u32 s30, s30, s31
	s_add_u32 s12, s90, s30
	s_addc_u32 s13, s91, 0
	s_add_u32 s12, s12, 0x6e200000
	s_addc_u32 s13, s13, 0
	s_lshl_b32 s31, s21, 8
	s_add_u32 s30, s16, s31
	s_addc_u32 s31, s17, 0
	global_load_dword v6, v1, s[30:31]
	s_lshl_b32 s31, s21, 8
	s_add_u32 s30, s18, s31
	s_addc_u32 s31, s19, 0
	global_load_dword v7, v1, s[30:31]
	s_cmp_eq_u32 s23, 0
	s_cbranch_scc1 .Lpo_nosr
	s_lshl_b32 s30, s21, 4
	s_add_u32 s30, s30, s23
	s_lshl_b32 s30, s30, 14
	s_add_u32 s30, s90, s30
	s_addc_u32 s31, s91, 0
	s_add_u32 s30, s30, 0x6fb00000
	s_addc_u32 s31, s31, 0
	global_load_dwordx4 v[16:19], v10, s[30:31]
	global_load_dwordx4 v[20:23], v10, s[30:31] offset:16
	global_load_dwordx4 v[24:27], v10, s[30:31] offset:32
	global_load_dwordx4 v[28:31], v10, s[30:31] offset:48
	global_load_dwordx4 v[32:35], v10, s[30:31] offset:64
	global_load_dwordx4 v[36:39], v10, s[30:31] offset:80
	global_load_dwordx4 v[40:43], v10, s[30:31] offset:96
	global_load_dwordx4 v[44:47], v10, s[30:31] offset:112
	global_load_dwordx4 v[48:51], v10, s[30:31] offset:128
	global_load_dwordx4 v[52:55], v10, s[30:31] offset:144
	global_load_dwordx4 v[56:59], v10, s[30:31] offset:160
	global_load_dwordx4 v[60:63], v10, s[30:31] offset:176
	global_load_dwordx4 v[64:67], v10, s[30:31] offset:192
	global_load_dwordx4 v[68:71], v10, s[30:31] offset:208
	global_load_dwordx4 v[72:75], v10, s[30:31] offset:224
	global_load_dwordx4 v[76:79], v10, s[30:31] offset:240
.Lpo_nosr:
	global_load_dwordx4 v[120:123], v11, s[6:7]
	global_load_dwordx4 v[124:127], v11, s[6:7] offset:1024
	global_load_dwordx4 v[128:131], v11, s[8:9]
	global_load_dwordx4 v[132:135], v11, s[8:9] offset:1024
	global_load_dwordx4 v[136:139], v11, s[14:15]
	global_load_dwordx4 v[140:143], v11, s[14:15] offset:1024
	global_load_dwordx4 v[144:147], v11, s[10:11]
	global_load_dword v148, v153, s[12:13]
	s_add_u32 s6, s6, 0x10000
	s_addc_u32 s7, s7, 0
	s_add_u32 s8, s8, 0x10000
	s_addc_u32 s9, s9, 0
	s_add_u32 s14, s14, 0x10000
	s_addc_u32 s15, s15, 0
	s_add_u32 s10, s10, 0x8000
	s_addc_u32 s11, s11, 0
	s_add_u32 s12, s12, 0x400
	s_addc_u32 s13, s13, 0
	s_waitcnt vmcnt(0)
	s_mov_b32 s25, 4
; #define LAS __attribute__((address_space(3)))
; #define POST_LD(Y_, V_, G_, R_, C_, t) do { _Pragma("unroll") for (int q = 0; q < 8; ++q) { const size_t o_ = (size_t)((t) + q) * DH; Y_[q] = yp[o_]; V_[q] = vp[o_]; G_[q] = gp[o_]; R_[q] = rp[((t) + q) * 32]; C_[q] = cp[o_]; } } while (0)
; __device__ __forceinline__ void rw_post(Frame& F) {
;     ...
;         POST_LD(y, vv, gg, rk, cc, 0);
;         for (int t0 = 0; t0 < 64; t0 += 8) {
;             float ny[8], nv[8], nr[8], nc[8]; bf16 ng[8];
;             const int tn = t0 + 8 < 64 ? t0 + 8 : t0;
;             POST_LD(ny, nv, ng, nr, nc, tn);
;             if (k > 0) {
;                 LAS float* cs = (LAS float*)(F.lds + 131072 + F.wave * 1024);
; #pragma unroll
;                 for (int hf = 0; hf < 2; ++hf) {
; #pragma unroll
;                     for (int q = 0; q < 4; ++q) cs[q * 64 + lane] = cc[4 * hf + q];
;                     asm volatile("s_waitcnt lgkmcnt(0)" ::: "memory");
; #pragma unroll
;                     for (int q = 0; q < 4; ++q) { f32x4 a = (f32x4){0.f, 0.f, 0.f, 0.f};
; #pragma unroll
;                         for (int i = 0; i < 16; ++i) a = __builtin_elementwise_fma(Sr[i], *(const LAS f32x4*)(cs + q * 64 + 4 * i), a);
;                         y[4 * hf + q] += (a[0] + a[1]) + (a[2] + a[3]); }
.Lpo_pair:
	s_waitcnt vmcnt(8)
	ds_write_b128 v12, v[120:123] offset:0
	ds_write_b128 v12, v[124:127] offset:1024
	ds_write_b128 v12, v[128:131] offset:16384
	ds_write_b128 v12, v[132:135] offset:17408
	ds_write_b128 v12, v[136:139] offset:32768
	ds_write_b128 v12, v[140:143] offset:33792
	ds_write_b128 v14, v[144:147]
	v_readlane_b32 s69, v148, 0
	v_readlane_b32 s70, v148, 1
	v_readlane_b32 s71, v148, 2
	v_readlane_b32 s72, v148, 3
	v_readlane_b32 s73, v148, 4
	v_readlane_b32 s26, v148, 5
	v_readlane_b32 s27, v148, 6
	v_readlane_b32 s32, v148, 7
	global_load_dwordx4 v[120:123], v11, s[6:7]
	global_load_dwordx4 v[124:127], v11, s[6:7] offset:1024
	global_load_dwordx4 v[128:131], v11, s[8:9]
	global_load_dwordx4 v[132:135], v11, s[8:9] offset:1024
	global_load_dwordx4 v[136:139], v11, s[14:15]
	global_load_dwordx4 v[140:143], v11, s[14:15] offset:1024
	global_load_dwordx4 v[144:147], v11, s[10:11]
	global_load_dword v148, v153, s[12:13]
	s_add_u32 s6, s6, 0x10000
	s_addc_u32 s7, s7, 0
	s_add_u32 s8, s8, 0x10000
	s_addc_u32 s9, s9, 0
	s_add_u32 s14, s14, 0x10000
	s_addc_u32 s15, s15, 0
	s_add_u32 s10, s10, 0x8000
	s_addc_u32 s11, s11, 0
	s_add_u32 s12, s12, 0x400
	s_addc_u32 s13, s13, 0
	s_waitcnt lgkmcnt(0)
	s_barrier
	ds_read_b32 v80, v149 offset:0
	ds_read_b32 v81, v149 offset:16384
	ds_read_b32 v82, v149 offset:32768
	ds_read_u16 v83, v151 offset:0
	ds_read_b32 v85, v149 offset:2048
	ds_read_b32 v86, v149 offset:18432
	ds_read_b32 v87, v149 offset:34816
	ds_read_u16 v88, v151 offset:1024
	ds_read_b32 v90, v149 offset:4096
	ds_read_b32 v91, v149 offset:20480
	ds_read_b32 v92, v149 offset:36864
	ds_read_u16 v93, v151 offset:2048
	ds_read_b32 v95, v149 offset:6144
	ds_read_b32 v96, v149 offset:22528
	ds_read_b32 v97, v149 offset:38912
	ds_read_u16 v98, v151 offset:3072
	ds_read_b32 v100, v149 offset:8192
	ds_read_b32 v101, v149 offset:24576
	ds_read_b32 v102, v149 offset:40960
	ds_read_u16 v103, v151 offset:4096
	ds_read_b32 v105, v149 offset:10240
	ds_read_b32 v106, v149 offset:26624
	ds_read_b32 v107, v149 offset:43008
	ds_read_u16 v108, v151 offset:5120
	ds_read_b32 v110, v149 offset:12288
	ds_read_b32 v111, v149 offset:28672
	ds_read_b32 v112, v149 offset:45056
	ds_read_u16 v113, v151 offset:6144
	ds_read_b32 v115, v149 offset:14336
	ds_read_b32 v116, v149 offset:30720
	ds_read_b32 v117, v149 offset:47104
	ds_read_u16 v118, v151 offset:7168
	s_waitcnt lgkmcnt(0)
	s_cmp_eq_u32 s23, 0
	s_cbranch_scc1 .Lpo_nc1
	ds_write_b32 v3, v82
	ds_write_b32 v3, v87 offset:256
	ds_write_b32 v3, v92 offset:512
	ds_write_b32 v3, v97 offset:768
	s_waitcnt lgkmcnt(0)
	ds_read_b128 v[204:207], v4 offset:0
	ds_read_b128 v[208:211], v4 offset:256
	ds_read_b128 v[212:215], v4 offset:512
	ds_read_b128 v[216:219], v4 offset:768
	ds_read_b128 v[220:223], v4 offset:16
	ds_read_b128 v[224:227], v4 offset:272
	ds_read_b128 v[228:231], v4 offset:528
	ds_read_b128 v[232:235], v4 offset:784
	s_waitcnt lgkmcnt(4)
	v_pk_mul_f32 v[184:185], v[16:17], v[204:205]
	v_pk_mul_f32 v[188:189], v[16:17], v[208:209]
	v_pk_mul_f32 v[192:193], v[16:17], v[212:213]
	v_pk_mul_f32 v[196:197], v[16:17], v[216:217]
	v_pk_mul_f32 v[186:187], v[18:19], v[206:207]
	v_pk_mul_f32 v[190:191], v[18:19], v[210:211]
	v_pk_mul_f32 v[194:195], v[18:19], v[214:215]
	v_pk_mul_f32 v[198:199], v[18:19], v[218:219]
	ds_read_b128 v[204:207], v4 offset:32
	ds_read_b128 v[208:211], v4 offset:288
	ds_read_b128 v[212:215], v4 offset:544
	ds_read_b128 v[216:219], v4 offset:800
	s_waitcnt lgkmcnt(4)
	v_pk_fma_f32 v[184:185], v[20:21], v[220:221], v[184:185]
	v_pk_fma_f32 v[188:189], v[20:21], v[224:225], v[188:189]
	v_pk_fma_f32 v[192:193], v[20:21], v[228:229], v[192:193]
	v_pk_fma_f32 v[196:197], v[20:21], v[232:233], v[196:197]
	v_pk_fma_f32 v[186:187], v[22:23], v[222:223], v[186:187]
	v_pk_fma_f32 v[190:191], v[22:23], v[226:227], v[190:191]
	v_pk_fma_f32 v[194:195], v[22:23], v[230:231], v[194:195]
	v_pk_fma_f32 v[198:199], v[22:23], v[234:235], v[198:199]
	ds_read_b128 v[220:223], v4 offset:48
	ds_read_b128 v[224:227], v4 offset:304
	ds_read_b128 v[228:231], v4 offset:560
	ds_read_b128 v[232:235], v4 offset:816
	s_waitcnt lgkmcnt(4)
	v_pk_fma_f32 v[184:185], v[24:25], v[204:205], v[184:185]
	v_pk_fma_f32 v[188:189], v[24:25], v[208:209], v[188:189]
	v_pk_fma_f32 v[192:193], v[24:25], v[212:213], v[192:193]
	v_pk_fma_f32 v[196:197], v[24:25], v[216:217], v[196:197]
	v_pk_fma_f32 v[186:187], v[26:27], v[206:207], v[186:187]
	v_pk_fma_f32 v[190:191], v[26:27], v[210:211], v[190:191]
	v_pk_fma_f32 v[194:195], v[26:27], v[214:215], v[194:195]
	v_pk_fma_f32 v[198:199], v[26:27], v[218:219], v[198:199]
	ds_read_b128 v[204:207], v4 offset:64
	ds_read_b128 v[208:211], v4 offset:320
	ds_read_b128 v[212:215], v4 offset:576
	ds_read_b128 v[216:219], v4 offset:832
	s_waitcnt lgkmcnt(4)
	v_pk_fma_f32 v[184:185], v[28:29], v[220:221], v[184:185]
	v_pk_fma_f32 v[188:189], v[28:29], v[224:225], v[188:189]
	v_pk_fma_f32 v[192:193], v[28:29], v[228:229], v[192:193]
	v_pk_fma_f32 v[196:197], v[28:29], v[232:233], v[196:197]
	v_pk_fma_f32 v[186:187], v[30:31], v[222:223], v[186:187]
	v_pk_fma_f32 v[190:191], v[30:31], v[226:227], v[190:191]
	v_pk_fma_f32 v[194:195], v[30:31], v[230:231], v[194:195]
	v_pk_fma_f32 v[198:199], v[30:31], v[234:235], v[198:199]
	ds_read_b128 v[220:223], v4 offset:80
	ds_read_b128 v[224:227], v4 offset:336
	ds_read_b128 v[228:231], v4 offset:592
	ds_read_b128 v[232:235], v4 offset:848
	s_waitcnt lgkmcnt(4)
; #define LAS __attribute__((address_space(3)))
; __device__ __forceinline__ void rw_post(Frame& F) {
;     ...
;                     for (int q = 0; q < 4; ++q) { f32x4 a = (f32x4){0.f, 0.f, 0.f, 0.f};
; #pragma unroll
;                         for (int i = 0; i < 16; ++i) a = __builtin_elementwise_fma(Sr[i], *(const LAS f32x4*)(cs + q * 64 + 4 * i), a);
;                         y[4 * hf + q] += (a[0] + a[1]) + (a[2] + a[3]); }
	v_pk_fma_f32 v[184:185], v[32:33], v[204:205], v[184:185]
	v_pk_fma_f32 v[188:189], v[32:33], v[208:209], v[188:189]
	v_pk_fma_f32 v[192:193], v[32:33], v[212:213], v[192:193]
	v_pk_fma_f32 v[196:197], v[32:33], v[216:217], v[196:197]
	v_pk_fma_f32 v[186:187], v[34:35], v[206:207], v[186:187]
	v_pk_fma_f32 v[190:191], v[34:35], v[210:211], v[190:191]
	v_pk_fma_f32 v[194:195], v[34:35], v[214:215], v[194:195]
	v_pk_fma_f32 v[198:199], v[34:35], v[218:219], v[198:199]
	ds_read_b128 v[204:207], v4 offset:96
	ds_read_b128 v[208:211], v4 offset:352
	ds_read_b128 v[212:215], v4 offset:608
	ds_read_b128 v[216:219], v4 offset:864
	s_waitcnt lgkmcnt(4)
	v_pk_fma_f32 v[184:185], v[36:37], v[220:221], v[184:185]
	v_pk_fma_f32 v[188:189], v[36:37], v[224:225], v[188:189]
	v_pk_fma_f32 v[192:193], v[36:37], v[228:229], v[192:193]
	v_pk_fma_f32 v[196:197], v[36:37], v[232:233], v[196:197]
	v_pk_fma_f32 v[186:187], v[38:39], v[222:223], v[186:187]
	v_pk_fma_f32 v[190:191], v[38:39], v[226:227], v[190:191]
	v_pk_fma_f32 v[194:195], v[38:39], v[230:231], v[194:195]
	v_pk_fma_f32 v[198:199], v[38:39], v[234:235], v[198:199]
	ds_read_b128 v[220:223], v4 offset:112
	ds_read_b128 v[224:227], v4 offset:368
	ds_read_b128 v[228:231], v4 offset:624
	ds_read_b128 v[232:235], v4 offset:880
	s_waitcnt lgkmcnt(4)
	v_pk_fma_f32 v[184:185], v[40:41], v[204:205], v[184:185]
	v_pk_fma_f32 v[188:189], v[40:41], v[208:209], v[188:189]
	v_pk_fma_f32 v[192:193], v[40:41], v[212:213], v[192:193]
	v_pk_fma_f32 v[196:197], v[40:41], v[216:217], v[196:197]
	v_pk_fma_f32 v[186:187], v[42:43], v[206:207], v[186:187]
	v_pk_fma_f32 v[190:191], v[42:43], v[210:211], v[190:191]
	v_pk_fma_f32 v[194:195], v[42:43], v[214:215], v[194:195]
	v_pk_fma_f32 v[198:199], v[42:43], v[218:219], v[198:199]
	ds_read_b128 v[204:207], v4 offset:128
	ds_read_b128 v[208:211], v4 offset:384
	ds_read_b128 v[212:215], v4 offset:640
	ds_read_b128 v[216:219], v4 offset:896
	s_waitcnt lgkmcnt(4)
	v_pk_fma_f32 v[184:185], v[44:45], v[220:221], v[184:185]
	v_pk_fma_f32 v[188:189], v[44:45], v[224:225], v[188:189]
	v_pk_fma_f32 v[192:193], v[44:45], v[228:229], v[192:193]
	v_pk_fma_f32 v[196:197], v[44:45], v[232:233], v[196:197]
	v_pk_fma_f32 v[186:187], v[46:47], v[222:223], v[186:187]
	v_pk_fma_f32 v[190:191], v[46:47], v[226:227], v[190:191]
	v_pk_fma_f32 v[194:195], v[46:47], v[230:231], v[194:195]
	v_pk_fma_f32 v[198:199], v[46:47], v[234:235], v[198:199]
	ds_read_b128 v[220:223], v4 offset:144
	ds_read_b128 v[224:227], v4 offset:400
	ds_read_b128 v[228:231], v4 offset:656
	ds_read_b128 v[232:235], v4 offset:912
	s_waitcnt lgkmcnt(4)
	v_pk_fma_f32 v[184:185], v[48:49], v[204:205], v[184:185]
	v_pk_fma_f32 v[188:189], v[48:49], v[208:209], v[188:189]
	v_pk_fma_f32 v[192:193], v[48:49], v[212:213], v[192:193]
	v_pk_fma_f32 v[196:197], v[48:49], v[216:217], v[196:197]
	v_pk_fma_f32 v[186:187], v[50:51], v[206:207], v[186:187]
	v_pk_fma_f32 v[190:191], v[50:51], v[210:211], v[190:191]
	v_pk_fma_f32 v[194:195], v[50:51], v[214:215], v[194:195]
	v_pk_fma_f32 v[198:199], v[50:51], v[218:219], v[198:199]
	ds_read_b128 v[204:207], v4 offset:160
	ds_read_b128 v[208:211], v4 offset:416
	ds_read_b128 v[212:215], v4 offset:672
	ds_read_b128 v[216:219], v4 offset:928
	s_waitcnt lgkmcnt(4)
	v_pk_fma_f32 v[184:185], v[52:53], v[220:221], v[184:185]
	v_pk_fma_f32 v[188:189], v[52:53], v[224:225], v[188:189]
	v_pk_fma_f32 v[192:193], v[52:53], v[228:229], v[192:193]
	v_pk_fma_f32 v[196:197], v[52:53], v[232:233], v[196:197]
	v_pk_fma_f32 v[186:187], v[54:55], v[222:223], v[186:187]
	v_pk_fma_f32 v[190:191], v[54:55], v[226:227], v[190:191]
	v_pk_fma_f32 v[194:195], v[54:55], v[230:231], v[194:195]
	v_pk_fma_f32 v[198:199], v[54:55], v[234:235], v[198:199]
	ds_read_b128 v[220:223], v4 offset:176
	ds_read_b128 v[224:227], v4 offset:432
	ds_read_b128 v[228:231], v4 offset:688
	ds_read_b128 v[232:235], v4 offset:944
	s_waitcnt lgkmcnt(4)
	v_pk_fma_f32 v[184:185], v[56:57], v[204:205], v[184:185]
	v_pk_fma_f32 v[188:189], v[56:57], v[208:209], v[188:189]
	v_pk_fma_f32 v[192:193], v[56:57], v[212:213], v[192:193]
	v_pk_fma_f32 v[196:197], v[56:57], v[216:217], v[196:197]
	v_pk_fma_f32 v[186:187], v[58:59], v[206:207], v[186:187]
	v_pk_fma_f32 v[190:191], v[58:59], v[210:211], v[190:191]
	v_pk_fma_f32 v[194:195], v[58:59], v[214:215], v[194:195]
	v_pk_fma_f32 v[198:199], v[58:59], v[218:219], v[198:199]
	ds_read_b128 v[204:207], v4 offset:192
	ds_read_b128 v[208:211], v4 offset:448
	ds_read_b128 v[212:215], v4 offset:704
	ds_read_b128 v[216:219], v4 offset:960
	s_waitcnt lgkmcnt(4)
	v_pk_fma_f32 v[184:185], v[60:61], v[220:221], v[184:185]
	v_pk_fma_f32 v[188:189], v[60:61], v[224:225], v[188:189]
	v_pk_fma_f32 v[192:193], v[60:61], v[228:229], v[192:193]
	v_pk_fma_f32 v[196:197], v[60:61], v[232:233], v[196:197]
	v_pk_fma_f32 v[186:187], v[62:63], v[222:223], v[186:187]
	v_pk_fma_f32 v[190:191], v[62:63], v[226:227], v[190:191]
	v_pk_fma_f32 v[194:195], v[62:63], v[230:231], v[194:195]
	v_pk_fma_f32 v[198:199], v[62:63], v[234:235], v[198:199]
	ds_read_b128 v[220:223], v4 offset:208
	ds_read_b128 v[224:227], v4 offset:464
	ds_read_b128 v[228:231], v4 offset:720
	ds_read_b128 v[232:235], v4 offset:976
	s_waitcnt lgkmcnt(4)
	v_pk_fma_f32 v[184:185], v[64:65], v[204:205], v[184:185]
	v_pk_fma_f32 v[188:189], v[64:65], v[208:209], v[188:189]
	v_pk_fma_f32 v[192:193], v[64:65], v[212:213], v[192:193]
	v_pk_fma_f32 v[196:197], v[64:65], v[216:217], v[196:197]
	v_pk_fma_f32 v[186:187], v[66:67], v[206:207], v[186:187]
	v_pk_fma_f32 v[190:191], v[66:67], v[210:211], v[190:191]
	v_pk_fma_f32 v[194:195], v[66:67], v[214:215], v[194:195]
	v_pk_fma_f32 v[198:199], v[66:67], v[218:219], v[198:199]
	ds_read_b128 v[204:207], v4 offset:224
	ds_read_b128 v[208:211], v4 offset:480
	ds_read_b128 v[212:215], v4 offset:736
	ds_read_b128 v[216:219], v4 offset:992
	s_waitcnt lgkmcnt(4)
; #define LAS __attribute__((address_space(3)))
; __device__ __forceinline__ float dpp_xor1(float x) { return __builtin_bit_cast(float, __builtin_amdgcn_update_dpp(0, __builtin_bit_cast(int, x), 0xB1, 0xF, 0xF, true)); }
; __device__ __forceinline__ float dpp_xor2(float x) { return __builtin_bit_cast(float, __builtin_amdgcn_update_dpp(0, __builtin_bit_cast(int, x), 0x4E, 0xF, 0xF, true)); }
; __device__ __forceinline__ float dpp_hmir(float x) { return __builtin_bit_cast(float, __builtin_amdgcn_update_dpp(0, __builtin_bit_cast(int, x), 0x141, 0xF, 0xF, true)); }
; __device__ __forceinline__ float dpp_mir(float x)  { return __builtin_bit_cast(float, __builtin_amdgcn_update_dpp(0, __builtin_bit_cast(int, x), 0x140, 0xF, 0xF, true)); }
; __device__ __forceinline__ float red16(float x) { x += dpp_xor1(x); x += dpp_xor2(x); x += dpp_hmir(x); x += dpp_mir(x); return x; }
; __device__ __forceinline__ float wsum(float x) {
;     x = red16(x); const int xi = __builtin_bit_cast(int, x);
;     const float r0 = __builtin_bit_cast(float, __builtin_amdgcn_readlane(xi, 0)), r1 = __builtin_bit_cast(float, __builtin_amdgcn_readlane(xi, 16));
;     const float r2 = __builtin_bit_cast(float, __builtin_amdgcn_readlane(xi, 32)), r3 = __builtin_bit_cast(float, __builtin_amdgcn_readlane(xi, 48));
;     return (r0 + r1) + (r2 + r3);
; __device__ __forceinline__ void rw_post(Frame& F) {
;     ...
;                     for (int q = 0; q < 4; ++q) { f32x4 a = (f32x4){0.f, 0.f, 0.f, 0.f};
; #pragma unroll
;                         for (int i = 0; i < 16; ++i) a = __builtin_elementwise_fma(Sr[i], *(const LAS f32x4*)(cs + q * 64 + 4 * i), a);
;                         y[4 * hf + q] += (a[0] + a[1]) + (a[2] + a[3]); }
;                     asm volatile("s_waitcnt lgkmcnt(0)" ::: "memory"); }
;             }
; #pragma unroll
;             for (int q = 0; q < 8; ++q) { const int row = rb0 + t0 + q;
;                 const float mean = wsum(y[q]) * (1.f / 64.f); const float dv = y[q] - mean; const float var = wsum(dv * dv) * (1.f / 64.f);
;                 const float yn = dv * (1.f / sqrtf(var + 64e-5f)) * g_ + b_;
	v_pk_fma_f32 v[184:185], v[68:69], v[220:221], v[184:185]
	v_pk_fma_f32 v[188:189], v[68:69], v[224:225], v[188:189]
	v_pk_fma_f32 v[192:193], v[68:69], v[228:229], v[192:193]
	v_pk_fma_f32 v[196:197], v[68:69], v[232:233], v[196:197]
	v_pk_fma_f32 v[186:187], v[70:71], v[222:223], v[186:187]
	v_pk_fma_f32 v[190:191], v[70:71], v[226:227], v[190:191]
	v_pk_fma_f32 v[194:195], v[70:71], v[230:231], v[194:195]
	v_pk_fma_f32 v[198:199], v[70:71], v[234:235], v[198:199]
	ds_read_b128 v[220:223], v4 offset:240
	ds_read_b128 v[224:227], v4 offset:496
	ds_read_b128 v[228:231], v4 offset:752
	ds_read_b128 v[232:235], v4 offset:1008
	s_waitcnt lgkmcnt(4)
	v_pk_fma_f32 v[184:185], v[72:73], v[204:205], v[184:185]
	v_pk_fma_f32 v[188:189], v[72:73], v[208:209], v[188:189]
	v_pk_fma_f32 v[192:193], v[72:73], v[212:213], v[192:193]
	v_pk_fma_f32 v[196:197], v[72:73], v[216:217], v[196:197]
	v_pk_fma_f32 v[186:187], v[74:75], v[206:207], v[186:187]
	v_pk_fma_f32 v[190:191], v[74:75], v[210:211], v[190:191]
	v_pk_fma_f32 v[194:195], v[74:75], v[214:215], v[194:195]
	v_pk_fma_f32 v[198:199], v[74:75], v[218:219], v[198:199]
	s_waitcnt lgkmcnt(0)
	v_pk_fma_f32 v[184:185], v[76:77], v[220:221], v[184:185]
	v_pk_fma_f32 v[188:189], v[76:77], v[224:225], v[188:189]
	v_pk_fma_f32 v[192:193], v[76:77], v[228:229], v[192:193]
	v_pk_fma_f32 v[196:197], v[76:77], v[232:233], v[196:197]
	v_pk_fma_f32 v[186:187], v[78:79], v[222:223], v[186:187]
	v_pk_fma_f32 v[190:191], v[78:79], v[226:227], v[190:191]
	v_pk_fma_f32 v[194:195], v[78:79], v[230:231], v[194:195]
	v_pk_fma_f32 v[198:199], v[78:79], v[234:235], v[198:199]
	v_add_f32_e32 v184, v184, v185
	v_add_f32_e32 v188, v188, v189
	v_add_f32_e32 v192, v192, v193
	v_add_f32_e32 v196, v196, v197
	v_add_f32_e32 v186, v186, v187
	v_add_f32_e32 v190, v190, v191
	v_add_f32_e32 v194, v194, v195
	v_add_f32_e32 v198, v198, v199
	v_add_f32_e32 v184, v184, v186
	v_add_f32_e32 v188, v188, v190
	v_add_f32_e32 v192, v192, v194
	v_add_f32_e32 v196, v196, v198
	v_add_f32_e32 v80, v80, v184
	v_add_f32_e32 v85, v85, v188
	v_add_f32_e32 v90, v90, v192
	v_add_f32_e32 v95, v95, v196
.Lpo_nc1:
	v_add_f32_dpp v168, v80, v80 quad_perm:[1,0,3,2] row_mask:0xf bank_mask:0xf bound_ctrl:1
	v_add_f32_dpp v174, v85, v85 quad_perm:[1,0,3,2] row_mask:0xf bank_mask:0xf bound_ctrl:1
	v_add_f32_dpp v241, v90, v90 quad_perm:[1,0,3,2] row_mask:0xf bank_mask:0xf bound_ctrl:1
	v_add_f32_dpp v247, v95, v95 quad_perm:[1,0,3,2] row_mask:0xf bank_mask:0xf bound_ctrl:1
	v_add_f32_dpp v168, v168, v168 quad_perm:[2,3,0,1] row_mask:0xf bank_mask:0xf bound_ctrl:1
	v_add_f32_dpp v174, v174, v174 quad_perm:[2,3,0,1] row_mask:0xf bank_mask:0xf bound_ctrl:1
	v_add_f32_dpp v241, v241, v241 quad_perm:[2,3,0,1] row_mask:0xf bank_mask:0xf bound_ctrl:1
	v_add_f32_dpp v247, v247, v247 quad_perm:[2,3,0,1] row_mask:0xf bank_mask:0xf bound_ctrl:1
	v_add_f32_dpp v168, v168, v168 row_half_mirror row_mask:0xf bank_mask:0xf bound_ctrl:1
	v_add_f32_dpp v174, v174, v174 row_half_mirror row_mask:0xf bank_mask:0xf bound_ctrl:1
	v_add_f32_dpp v241, v241, v241 row_half_mirror row_mask:0xf bank_mask:0xf bound_ctrl:1
	v_add_f32_dpp v247, v247, v247 row_half_mirror row_mask:0xf bank_mask:0xf bound_ctrl:1
	v_add_f32_dpp v168, v168, v168 row_mirror row_mask:0xf bank_mask:0xf bound_ctrl:1
	v_add_f32_dpp v174, v174, v174 row_mirror row_mask:0xf bank_mask:0xf bound_ctrl:1
	v_add_f32_dpp v241, v241, v241 row_mirror row_mask:0xf bank_mask:0xf bound_ctrl:1
	v_add_f32_dpp v247, v247, v247 row_mirror row_mask:0xf bank_mask:0xf bound_ctrl:1
	v_readlane_b32 s36, v168, 16
	v_readlane_b32 s40, v174, 16
	v_readlane_b32 s44, v241, 16
	v_readlane_b32 s48, v247, 16
	v_readlane_b32 s37, v168, 48
	v_readlane_b32 s41, v174, 48
	v_readlane_b32 s45, v241, 48
	v_readlane_b32 s49, v247, 48
	v_readlane_b32 s38, v168, 0
	v_readlane_b32 s42, v174, 0
	v_readlane_b32 s46, v241, 0
	v_readlane_b32 s50, v247, 0
	v_readlane_b32 s39, v168, 32
	v_readlane_b32 s43, v174, 32
	v_readlane_b32 s47, v241, 32
	v_readlane_b32 s51, v247, 32
	v_mov_b32_e32 v168, s36
	v_mov_b32_e32 v174, s40
	v_mov_b32_e32 v241, s44
	v_mov_b32_e32 v247, s48
	v_mov_b32_e32 v169, s37
	v_mov_b32_e32 v175, s41
	v_mov_b32_e32 v242, s45
	v_mov_b32_e32 v248, s49
	v_add_f32_e32 v168, s38, v168
	v_add_f32_e32 v174, s42, v174
	v_add_f32_e32 v241, s46, v241
	v_add_f32_e32 v247, s50, v247
	v_add_f32_e32 v169, s39, v169
	v_add_f32_e32 v175, s43, v175
	v_add_f32_e32 v242, s47, v242
	v_add_f32_e32 v248, s51, v248
	v_add_f32_e32 v168, v168, v169
	v_add_f32_e32 v174, v174, v175
	v_add_f32_e32 v241, v241, v242
	v_add_f32_e32 v247, v247, v248
	v_fmamk_f32 v80, v168, 0xbc800000, v80
	v_fmamk_f32 v85, v174, 0xbc800000, v85
	v_fmamk_f32 v90, v241, 0xbc800000, v90
	v_fmamk_f32 v95, v247, 0xbc800000, v95
	v_mul_f32_e32 v168, v80, v80
	v_mul_f32_e32 v174, v85, v85
	v_mul_f32_e32 v241, v90, v90
	v_mul_f32_e32 v247, v95, v95
	v_mov_b32_dpp v168, v168 quad_perm:[1,0,3,2] row_mask:0xf bank_mask:0xf bound_ctrl:1
	v_mov_b32_dpp v174, v174 quad_perm:[1,0,3,2] row_mask:0xf bank_mask:0xf bound_ctrl:1
	v_mov_b32_dpp v241, v241 quad_perm:[1,0,3,2] row_mask:0xf bank_mask:0xf bound_ctrl:1
	v_mov_b32_dpp v247, v247 quad_perm:[1,0,3,2] row_mask:0xf bank_mask:0xf bound_ctrl:1
	v_fmac_f32_e32 v168, v80, v80
	v_fmac_f32_e32 v174, v85, v85
	v_fmac_f32_e32 v241, v90, v90
	v_fmac_f32_e32 v247, v95, v95
	v_add_f32_dpp v168, v168, v168 quad_perm:[2,3,0,1] row_mask:0xf bank_mask:0xf bound_ctrl:1
	v_add_f32_dpp v174, v174, v174 quad_perm:[2,3,0,1] row_mask:0xf bank_mask:0xf bound_ctrl:1
	v_add_f32_dpp v241, v241, v241 quad_perm:[2,3,0,1] row_mask:0xf bank_mask:0xf bound_ctrl:1
; __device__ __forceinline__ void rw_post(Frame& F) {
;     ...
;                 const float mean = wsum(y[q]) * (1.f / 64.f); const float dv = y[q] - mean; const float var = wsum(dv * dv) * (1.f / 64.f);
;                 const float yn = dv * (1.f / sqrtf(var + 64e-5f)) * g_ + b_;
	v_add_f32_dpp v247, v247, v247 quad_perm:[2,3,0,1] row_mask:0xf bank_mask:0xf bound_ctrl:1
	v_add_f32_dpp v168, v168, v168 row_half_mirror row_mask:0xf bank_mask:0xf bound_ctrl:1
	v_add_f32_dpp v174, v174, v174 row_half_mirror row_mask:0xf bank_mask:0xf bound_ctrl:1
	v_add_f32_dpp v241, v241, v241 row_half_mirror row_mask:0xf bank_mask:0xf bound_ctrl:1
	v_add_f32_dpp v247, v247, v247 row_half_mirror row_mask:0xf bank_mask:0xf bound_ctrl:1
	v_add_f32_dpp v168, v168, v168 row_mirror row_mask:0xf bank_mask:0xf bound_ctrl:1
	v_add_f32_dpp v174, v174, v174 row_mirror row_mask:0xf bank_mask:0xf bound_ctrl:1
	v_add_f32_dpp v241, v241, v241 row_mirror row_mask:0xf bank_mask:0xf bound_ctrl:1
	v_add_f32_dpp v247, v247, v247 row_mirror row_mask:0xf bank_mask:0xf bound_ctrl:1
	v_readlane_b32 s36, v168, 16
	v_readlane_b32 s40, v174, 16
	v_readlane_b32 s44, v241, 16
	v_readlane_b32 s48, v247, 16
	v_readlane_b32 s37, v168, 48
	v_readlane_b32 s41, v174, 48
	v_readlane_b32 s45, v241, 48
	v_readlane_b32 s49, v247, 48
	v_readlane_b32 s38, v168, 0
	v_readlane_b32 s42, v174, 0
	v_readlane_b32 s46, v241, 0
	v_readlane_b32 s50, v247, 0
	v_readlane_b32 s39, v168, 32
	v_readlane_b32 s43, v174, 32
	v_readlane_b32 s47, v241, 32
	v_readlane_b32 s51, v247, 32
	v_mov_b32_e32 v168, s36
	v_mov_b32_e32 v174, s40
	v_mov_b32_e32 v241, s44
	v_mov_b32_e32 v247, s48
	v_mov_b32_e32 v169, s37
	v_mov_b32_e32 v175, s41
	v_mov_b32_e32 v242, s45
	v_mov_b32_e32 v248, s49
	v_add_f32_e32 v168, s38, v168
	v_add_f32_e32 v174, s42, v174
	v_add_f32_e32 v241, s46, v241
	v_add_f32_e32 v247, s50, v247
	v_add_f32_e32 v169, s39, v169
	v_add_f32_e32 v175, s43, v175
	v_add_f32_e32 v242, s47, v242
	v_add_f32_e32 v248, s51, v248
	v_add_f32_e32 v168, v168, v169
	v_add_f32_e32 v174, v174, v175
	v_add_f32_e32 v241, v241, v242
	v_add_f32_e32 v247, v247, v248
	v_fmamk_f32 v168, v168, 0x3c800000, v9
	v_fmamk_f32 v174, v174, 0x3c800000, v9
	v_fmamk_f32 v241, v241, 0x3c800000, v9
	v_fmamk_f32 v247, v247, 0x3c800000, v9
	v_mul_f32_e32 v169, 0x4f800000, v168
	v_mul_f32_e32 v175, 0x4f800000, v174
	v_mul_f32_e32 v242, 0x4f800000, v241
	v_mul_f32_e32 v248, 0x4f800000, v247
	v_cmp_gt_f32_e64 s[52:53], s68, v168
	v_cmp_gt_f32_e64 s[54:55], s68, v174
	v_cmp_gt_f32_e64 s[56:57], s68, v241
	v_cmp_gt_f32_e64 s[58:59], s68, v247
	v_mov_b32_e32 v170, v168
	v_mov_b32_e32 v176, v174
	v_mov_b32_e32 v243, v241
	v_mov_b32_e32 v249, v247
	v_cndmask_b32_e64 v168, v170, v169, s[52:53]
	v_cndmask_b32_e64 v174, v176, v175, s[54:55]
	v_cndmask_b32_e64 v241, v243, v242, s[56:57]
	v_cndmask_b32_e64 v247, v249, v248, s[58:59]
	v_sqrt_f32_e32 v169, v168
	v_sqrt_f32_e32 v175, v174
	v_sqrt_f32_e32 v242, v241
	v_sqrt_f32_e32 v248, v247
	v_add_u32_e32 v170, -1, v169
	v_add_u32_e32 v176, -1, v175
	v_add_u32_e32 v243, -1, v242
	v_add_u32_e32 v249, -1, v248
	v_fma_f32 v171, -v170, v169, v168
	v_fma_f32 v177, -v176, v175, v174
	v_fma_f32 v244, -v243, v242, v241
	v_fma_f32 v250, -v249, v248, v247
	v_cmp_ge_f32_e64 s[60:61], 0, v171
	v_cmp_ge_f32_e64 s[62:63], 0, v177
	v_cmp_ge_f32_e64 s[64:65], 0, v244
	v_cmp_ge_f32_e64 s[66:67], 0, v250
	v_add_u32_e32 v171, 1, v169
	v_add_u32_e32 v177, 1, v175
	v_add_u32_e32 v244, 1, v242
	v_add_u32_e32 v250, 1, v248
	v_cndmask_b32_e64 v170, v169, v170, s[60:61]
	v_cndmask_b32_e64 v176, v175, v176, s[62:63]
	v_cndmask_b32_e64 v243, v242, v243, s[64:65]
	v_cndmask_b32_e64 v249, v248, v249, s[66:67]
	v_fma_f32 v169, -v171, v169, v168
	v_fma_f32 v175, -v177, v175, v174
	v_fma_f32 v242, -v244, v242, v241
	v_fma_f32 v248, -v250, v248, v247
	v_cmp_lt_f32_e64 s[60:61], 0, v169
	v_cmp_lt_f32_e64 s[62:63], 0, v175
	v_cmp_lt_f32_e64 s[64:65], 0, v242
	v_cmp_lt_f32_e64 s[66:67], 0, v248
	v_cndmask_b32_e64 v169, v170, v171, s[60:61]
	v_cndmask_b32_e64 v175, v176, v177, s[62:63]
	v_cndmask_b32_e64 v242, v243, v244, s[64:65]
	v_cndmask_b32_e64 v248, v249, v250, s[66:67]
	v_mul_f32_e32 v170, 0x37800000, v169
	v_mul_f32_e32 v176, 0x37800000, v175
	v_mul_f32_e32 v243, 0x37800000, v242
	v_mul_f32_e32 v249, 0x37800000, v248
	v_cndmask_b32_e64 v169, v169, v170, s[52:53]
	v_cndmask_b32_e64 v175, v175, v176, s[54:55]
	v_cndmask_b32_e64 v242, v242, v243, s[56:57]
	v_cndmask_b32_e64 v248, v248, v249, s[58:59]
	v_cmp_class_f32_e64 s[60:61], v168, v8
	v_cmp_class_f32_e64 s[62:63], v174, v8
	v_cmp_class_f32_e64 s[64:65], v241, v8
	v_cmp_class_f32_e64 s[66:67], v247, v8
	v_cndmask_b32_e64 v168, v169, v168, s[60:61]
	v_cndmask_b32_e64 v174, v175, v174, s[62:63]
	v_cndmask_b32_e64 v241, v242, v241, s[64:65]
	v_cndmask_b32_e64 v247, v248, v247, s[66:67]
	v_div_scale_f32 v169, s[60:61], v168, v168, 1.0
	v_rcp_f32_e32 v170, v169
	s_nop 0
	v_fma_f32 v171, -v169, v170, 1.0
	v_fmac_f32_e32 v170, v171, v170
	v_div_scale_f32 v171, vcc, 1.0, v168, 1.0
	v_mul_f32_e32 v172, v171, v170
	v_fma_f32 v173, -v169, v172, v171
	v_fmac_f32_e32 v172, v173, v170
	v_fma_f32 v169, -v169, v172, v171
	v_div_fmas_f32 v169, v169, v170, v172
	v_div_fixup_f32 v168, v169, v168, 1.0
	v_div_scale_f32 v175, s[62:63], v174, v174, 1.0
	v_rcp_f32_e32 v176, v175
	s_nop 0
	v_fma_f32 v177, -v175, v176, 1.0
	v_fmac_f32_e32 v176, v177, v176
	v_div_scale_f32 v177, vcc, 1.0, v174, 1.0
	v_mul_f32_e32 v236, v177, v176
	v_fma_f32 v237, -v175, v236, v177
	v_fmac_f32_e32 v236, v237, v176
	v_fma_f32 v175, -v175, v236, v177
	v_div_fmas_f32 v175, v175, v176, v236
	v_div_fixup_f32 v174, v175, v174, 1.0
	v_div_scale_f32 v242, s[64:65], v241, v241, 1.0
	v_rcp_f32_e32 v243, v242
	s_nop 0
	v_fma_f32 v244, -v242, v243, 1.0
	v_fmac_f32_e32 v243, v244, v243
	v_div_scale_f32 v244, vcc, 1.0, v241, 1.0
	v_mul_f32_e32 v245, v244, v243
	v_fma_f32 v246, -v242, v245, v244
	v_fmac_f32_e32 v245, v246, v243
; #define LAS __attribute__((address_space(3)))
; __device__ __forceinline__ float bf2f(bf16 x) { return __uint_as_float(((unsigned)x) << 16); }
; __device__ __forceinline__ unsigned f2bf(float f) { return cvt_pk_bf16(f, 0.f) & 0xffffu; }
; __device__ __forceinline__ void rw_post(Frame& F) {
;     ...
;                 for (int hf = 0; hf < 2; ++hf) {
; #pragma unroll
;                     for (int q = 0; q < 4; ++q) cs[q * 64 + lane] = cc[4 * hf + q];
;                     asm volatile("s_waitcnt lgkmcnt(0)" ::: "memory");
; #pragma unroll
;                     for (int q = 0; q < 4; ++q) { f32x4 a = (f32x4){0.f, 0.f, 0.f, 0.f};
; #pragma unroll
;                         for (int i = 0; i < 16; ++i) a = __builtin_elementwise_fma(Sr[i], *(const LAS f32x4*)(cs + q * 64 + 4 * i), a);
;                         y[4 * hf + q] += (a[0] + a[1]) + (a[2] + a[3]); }
;     ...
;             for (int q = 0; q < 8; ++q) { const int row = rb0 + t0 + q;
;                 const float mean = wsum(y[q]) * (1.f / 64.f); const float dv = y[q] - mean; const float var = wsum(dv * dv) * (1.f / 64.f);
;                 const float yn = dv * (1.f / sqrtf(var + 64e-5f)) * g_ + b_;
;                 OB[(size_t)row * DH + col] = (bf16)f2bf((yn + rk[q] * vv[q]) * bf2f(gg[q])); }
	v_fma_f32 v242, -v242, v245, v244
	v_div_fmas_f32 v242, v242, v243, v245
	v_div_fixup_f32 v241, v242, v241, 1.0
	v_div_scale_f32 v248, s[66:67], v247, v247, 1.0
	v_rcp_f32_e32 v249, v248
	s_nop 0
	v_fma_f32 v250, -v248, v249, 1.0
	v_fmac_f32_e32 v249, v250, v249
	v_div_scale_f32 v250, vcc, 1.0, v247, 1.0
	v_mul_f32_e32 v251, v250, v249
	v_fma_f32 v252, -v248, v251, v250
	v_fmac_f32_e32 v251, v252, v249
	v_fma_f32 v248, -v248, v251, v250
	v_div_fmas_f32 v248, v248, v249, v251
	v_div_fixup_f32 v247, v248, v247, 1.0
	v_mul_f32_e32 v80, v80, v168
	v_mul_f32_e32 v85, v85, v174
	v_mul_f32_e32 v90, v90, v241
	v_mul_f32_e32 v95, v95, v247
	v_lshlrev_b32_e32 v83, 16, v83
	v_lshlrev_b32_e32 v88, 16, v88
	v_lshlrev_b32_e32 v93, 16, v93
	v_lshlrev_b32_e32 v98, 16, v98
	v_fma_f32 v80, v6, v80, v7
	v_fma_f32 v85, v6, v85, v7
	v_fma_f32 v90, v6, v90, v7
	v_fma_f32 v95, v6, v95, v7
	v_fmac_f32_e32 v80, s69, v81
	v_fmac_f32_e32 v85, s70, v86
	v_fmac_f32_e32 v90, s71, v91
	v_fmac_f32_e32 v95, s72, v96
	v_mul_f32_e32 v80, v80, v83
	v_mul_f32_e32 v85, v85, v88
	v_mul_f32_e32 v90, v90, v93
	v_mul_f32_e32 v95, v95, v98
	v_cvt_pk_bf16_f32 v169, v80, v80
	v_cvt_pk_bf16_f32 v175, v85, v85
	v_cvt_pk_bf16_f32 v242, v90, v90
	v_cvt_pk_bf16_f32 v248, v95, v95
	global_store_short v2, v169, s[28:29]
	s_add_u32 s28, s28, 0x1000
	s_addc_u32 s29, s29, 0
	global_store_short v2, v175, s[28:29]
	s_add_u32 s28, s28, 0x1000
	s_addc_u32 s29, s29, 0
	global_store_short v2, v242, s[28:29]
	s_add_u32 s28, s28, 0x1000
	s_addc_u32 s29, s29, 0
	global_store_short v2, v248, s[28:29]
	s_add_u32 s28, s28, 0x1000
	s_addc_u32 s29, s29, 0
	s_cmp_eq_u32 s23, 0
	s_cbranch_scc1 .Lpo_nc2
	ds_write_b32 v3, v102
	ds_write_b32 v3, v107 offset:256
	ds_write_b32 v3, v112 offset:512
	ds_write_b32 v3, v117 offset:768
	s_waitcnt lgkmcnt(0)
	ds_read_b128 v[204:207], v4 offset:0
	ds_read_b128 v[208:211], v4 offset:256
	ds_read_b128 v[212:215], v4 offset:512
	ds_read_b128 v[216:219], v4 offset:768
	ds_read_b128 v[220:223], v4 offset:16
	ds_read_b128 v[224:227], v4 offset:272
	ds_read_b128 v[228:231], v4 offset:528
	ds_read_b128 v[232:235], v4 offset:784
	s_waitcnt lgkmcnt(4)
	v_pk_mul_f32 v[184:185], v[16:17], v[204:205]
	v_pk_mul_f32 v[188:189], v[16:17], v[208:209]
	v_pk_mul_f32 v[192:193], v[16:17], v[212:213]
	v_pk_mul_f32 v[196:197], v[16:17], v[216:217]
	v_pk_mul_f32 v[186:187], v[18:19], v[206:207]
	v_pk_mul_f32 v[190:191], v[18:19], v[210:211]
	v_pk_mul_f32 v[194:195], v[18:19], v[214:215]
	v_pk_mul_f32 v[198:199], v[18:19], v[218:219]
	ds_read_b128 v[204:207], v4 offset:32
	ds_read_b128 v[208:211], v4 offset:288
	ds_read_b128 v[212:215], v4 offset:544
	ds_read_b128 v[216:219], v4 offset:800
	s_waitcnt lgkmcnt(4)
	v_pk_fma_f32 v[184:185], v[20:21], v[220:221], v[184:185]
	v_pk_fma_f32 v[188:189], v[20:21], v[224:225], v[188:189]
	v_pk_fma_f32 v[192:193], v[20:21], v[228:229], v[192:193]
	v_pk_fma_f32 v[196:197], v[20:21], v[232:233], v[196:197]
	v_pk_fma_f32 v[186:187], v[22:23], v[222:223], v[186:187]
	v_pk_fma_f32 v[190:191], v[22:23], v[226:227], v[190:191]
	v_pk_fma_f32 v[194:195], v[22:23], v[230:231], v[194:195]
	v_pk_fma_f32 v[198:199], v[22:23], v[234:235], v[198:199]
	ds_read_b128 v[220:223], v4 offset:48
	ds_read_b128 v[224:227], v4 offset:304
	ds_read_b128 v[228:231], v4 offset:560
	ds_read_b128 v[232:235], v4 offset:816
	s_waitcnt lgkmcnt(4)
	v_pk_fma_f32 v[184:185], v[24:25], v[204:205], v[184:185]
	v_pk_fma_f32 v[188:189], v[24:25], v[208:209], v[188:189]
	v_pk_fma_f32 v[192:193], v[24:25], v[212:213], v[192:193]
	v_pk_fma_f32 v[196:197], v[24:25], v[216:217], v[196:197]
	v_pk_fma_f32 v[186:187], v[26:27], v[206:207], v[186:187]
	v_pk_fma_f32 v[190:191], v[26:27], v[210:211], v[190:191]
	v_pk_fma_f32 v[194:195], v[26:27], v[214:215], v[194:195]
	v_pk_fma_f32 v[198:199], v[26:27], v[218:219], v[198:199]
	ds_read_b128 v[204:207], v4 offset:64
	ds_read_b128 v[208:211], v4 offset:320
	ds_read_b128 v[212:215], v4 offset:576
	ds_read_b128 v[216:219], v4 offset:832
	s_waitcnt lgkmcnt(4)
	v_pk_fma_f32 v[184:185], v[28:29], v[220:221], v[184:185]
	v_pk_fma_f32 v[188:189], v[28:29], v[224:225], v[188:189]
	v_pk_fma_f32 v[192:193], v[28:29], v[228:229], v[192:193]
	v_pk_fma_f32 v[196:197], v[28:29], v[232:233], v[196:197]
	v_pk_fma_f32 v[186:187], v[30:31], v[222:223], v[186:187]
	v_pk_fma_f32 v[190:191], v[30:31], v[226:227], v[190:191]
	v_pk_fma_f32 v[194:195], v[30:31], v[230:231], v[194:195]
	v_pk_fma_f32 v[198:199], v[30:31], v[234:235], v[198:199]
	ds_read_b128 v[220:223], v4 offset:80
	ds_read_b128 v[224:227], v4 offset:336
	ds_read_b128 v[228:231], v4 offset:592
	ds_read_b128 v[232:235], v4 offset:848
	s_waitcnt lgkmcnt(4)
	v_pk_fma_f32 v[184:185], v[32:33], v[204:205], v[184:185]
	v_pk_fma_f32 v[188:189], v[32:33], v[208:209], v[188:189]
	v_pk_fma_f32 v[192:193], v[32:33], v[212:213], v[192:193]
	v_pk_fma_f32 v[196:197], v[32:33], v[216:217], v[196:197]
	v_pk_fma_f32 v[186:187], v[34:35], v[206:207], v[186:187]
	v_pk_fma_f32 v[190:191], v[34:35], v[210:211], v[190:191]
	v_pk_fma_f32 v[194:195], v[34:35], v[214:215], v[194:195]
	v_pk_fma_f32 v[198:199], v[34:35], v[218:219], v[198:199]
	ds_read_b128 v[204:207], v4 offset:96
	ds_read_b128 v[208:211], v4 offset:352
	ds_read_b128 v[212:215], v4 offset:608
	ds_read_b128 v[216:219], v4 offset:864
	s_waitcnt lgkmcnt(4)
; #define LAS __attribute__((address_space(3)))
; __device__ __forceinline__ void rw_post(Frame& F) {
;     ...
;                     for (int q = 0; q < 4; ++q) { f32x4 a = (f32x4){0.f, 0.f, 0.f, 0.f};
; #pragma unroll
;                         for (int i = 0; i < 16; ++i) a = __builtin_elementwise_fma(Sr[i], *(const LAS f32x4*)(cs + q * 64 + 4 * i), a);
;                         y[4 * hf + q] += (a[0] + a[1]) + (a[2] + a[3]); }
	v_pk_fma_f32 v[184:185], v[36:37], v[220:221], v[184:185]
	v_pk_fma_f32 v[188:189], v[36:37], v[224:225], v[188:189]
	v_pk_fma_f32 v[192:193], v[36:37], v[228:229], v[192:193]
	v_pk_fma_f32 v[196:197], v[36:37], v[232:233], v[196:197]
	v_pk_fma_f32 v[186:187], v[38:39], v[222:223], v[186:187]
	v_pk_fma_f32 v[190:191], v[38:39], v[226:227], v[190:191]
	v_pk_fma_f32 v[194:195], v[38:39], v[230:231], v[194:195]
	v_pk_fma_f32 v[198:199], v[38:39], v[234:235], v[198:199]
	ds_read_b128 v[220:223], v4 offset:112
	ds_read_b128 v[224:227], v4 offset:368
	ds_read_b128 v[228:231], v4 offset:624
	ds_read_b128 v[232:235], v4 offset:880
	s_waitcnt lgkmcnt(4)
	v_pk_fma_f32 v[184:185], v[40:41], v[204:205], v[184:185]
	v_pk_fma_f32 v[188:189], v[40:41], v[208:209], v[188:189]
	v_pk_fma_f32 v[192:193], v[40:41], v[212:213], v[192:193]
	v_pk_fma_f32 v[196:197], v[40:41], v[216:217], v[196:197]
	v_pk_fma_f32 v[186:187], v[42:43], v[206:207], v[186:187]
	v_pk_fma_f32 v[190:191], v[42:43], v[210:211], v[190:191]
	v_pk_fma_f32 v[194:195], v[42:43], v[214:215], v[194:195]
	v_pk_fma_f32 v[198:199], v[42:43], v[218:219], v[198:199]
	ds_read_b128 v[204:207], v4 offset:128
	ds_read_b128 v[208:211], v4 offset:384
	ds_read_b128 v[212:215], v4 offset:640
	ds_read_b128 v[216:219], v4 offset:896
	s_waitcnt lgkmcnt(4)
	v_pk_fma_f32 v[184:185], v[44:45], v[220:221], v[184:185]
	v_pk_fma_f32 v[188:189], v[44:45], v[224:225], v[188:189]
	v_pk_fma_f32 v[192:193], v[44:45], v[228:229], v[192:193]
	v_pk_fma_f32 v[196:197], v[44:45], v[232:233], v[196:197]
	v_pk_fma_f32 v[186:187], v[46:47], v[222:223], v[186:187]
	v_pk_fma_f32 v[190:191], v[46:47], v[226:227], v[190:191]
	v_pk_fma_f32 v[194:195], v[46:47], v[230:231], v[194:195]
	v_pk_fma_f32 v[198:199], v[46:47], v[234:235], v[198:199]
	ds_read_b128 v[220:223], v4 offset:144
	ds_read_b128 v[224:227], v4 offset:400
	ds_read_b128 v[228:231], v4 offset:656
	ds_read_b128 v[232:235], v4 offset:912
	s_waitcnt lgkmcnt(4)
	v_pk_fma_f32 v[184:185], v[48:49], v[204:205], v[184:185]
	v_pk_fma_f32 v[188:189], v[48:49], v[208:209], v[188:189]
	v_pk_fma_f32 v[192:193], v[48:49], v[212:213], v[192:193]
	v_pk_fma_f32 v[196:197], v[48:49], v[216:217], v[196:197]
	v_pk_fma_f32 v[186:187], v[50:51], v[206:207], v[186:187]
	v_pk_fma_f32 v[190:191], v[50:51], v[210:211], v[190:191]
	v_pk_fma_f32 v[194:195], v[50:51], v[214:215], v[194:195]
	v_pk_fma_f32 v[198:199], v[50:51], v[218:219], v[198:199]
	ds_read_b128 v[204:207], v4 offset:160
	ds_read_b128 v[208:211], v4 offset:416
	ds_read_b128 v[212:215], v4 offset:672
	ds_read_b128 v[216:219], v4 offset:928
	s_waitcnt lgkmcnt(4)
	v_pk_fma_f32 v[184:185], v[52:53], v[220:221], v[184:185]
	v_pk_fma_f32 v[188:189], v[52:53], v[224:225], v[188:189]
	v_pk_fma_f32 v[192:193], v[52:53], v[228:229], v[192:193]
	v_pk_fma_f32 v[196:197], v[52:53], v[232:233], v[196:197]
	v_pk_fma_f32 v[186:187], v[54:55], v[222:223], v[186:187]
	v_pk_fma_f32 v[190:191], v[54:55], v[226:227], v[190:191]
	v_pk_fma_f32 v[194:195], v[54:55], v[230:231], v[194:195]
	v_pk_fma_f32 v[198:199], v[54:55], v[234:235], v[198:199]
	ds_read_b128 v[220:223], v4 offset:176
	ds_read_b128 v[224:227], v4 offset:432
	ds_read_b128 v[228:231], v4 offset:688
	ds_read_b128 v[232:235], v4 offset:944
	s_waitcnt lgkmcnt(4)
	v_pk_fma_f32 v[184:185], v[56:57], v[204:205], v[184:185]
	v_pk_fma_f32 v[188:189], v[56:57], v[208:209], v[188:189]
	v_pk_fma_f32 v[192:193], v[56:57], v[212:213], v[192:193]
	v_pk_fma_f32 v[196:197], v[56:57], v[216:217], v[196:197]
	v_pk_fma_f32 v[186:187], v[58:59], v[206:207], v[186:187]
	v_pk_fma_f32 v[190:191], v[58:59], v[210:211], v[190:191]
	v_pk_fma_f32 v[194:195], v[58:59], v[214:215], v[194:195]
	v_pk_fma_f32 v[198:199], v[58:59], v[218:219], v[198:199]
	ds_read_b128 v[204:207], v4 offset:192
	ds_read_b128 v[208:211], v4 offset:448
	ds_read_b128 v[212:215], v4 offset:704
	ds_read_b128 v[216:219], v4 offset:960
	s_waitcnt lgkmcnt(4)
	v_pk_fma_f32 v[184:185], v[60:61], v[220:221], v[184:185]
	v_pk_fma_f32 v[188:189], v[60:61], v[224:225], v[188:189]
	v_pk_fma_f32 v[192:193], v[60:61], v[228:229], v[192:193]
	v_pk_fma_f32 v[196:197], v[60:61], v[232:233], v[196:197]
	v_pk_fma_f32 v[186:187], v[62:63], v[222:223], v[186:187]
	v_pk_fma_f32 v[190:191], v[62:63], v[226:227], v[190:191]
	v_pk_fma_f32 v[194:195], v[62:63], v[230:231], v[194:195]
	v_pk_fma_f32 v[198:199], v[62:63], v[234:235], v[198:199]
	ds_read_b128 v[220:223], v4 offset:208
	ds_read_b128 v[224:227], v4 offset:464
	ds_read_b128 v[228:231], v4 offset:720
	ds_read_b128 v[232:235], v4 offset:976
	s_waitcnt lgkmcnt(4)
	v_pk_fma_f32 v[184:185], v[64:65], v[204:205], v[184:185]
	v_pk_fma_f32 v[188:189], v[64:65], v[208:209], v[188:189]
	v_pk_fma_f32 v[192:193], v[64:65], v[212:213], v[192:193]
	v_pk_fma_f32 v[196:197], v[64:65], v[216:217], v[196:197]
	v_pk_fma_f32 v[186:187], v[66:67], v[206:207], v[186:187]
	v_pk_fma_f32 v[190:191], v[66:67], v[210:211], v[190:191]
	v_pk_fma_f32 v[194:195], v[66:67], v[214:215], v[194:195]
	v_pk_fma_f32 v[198:199], v[66:67], v[218:219], v[198:199]
	ds_read_b128 v[204:207], v4 offset:224
	ds_read_b128 v[208:211], v4 offset:480
	ds_read_b128 v[212:215], v4 offset:736
	ds_read_b128 v[216:219], v4 offset:992
	s_waitcnt lgkmcnt(4)
	v_pk_fma_f32 v[184:185], v[68:69], v[220:221], v[184:185]
	v_pk_fma_f32 v[188:189], v[68:69], v[224:225], v[188:189]
	v_pk_fma_f32 v[192:193], v[68:69], v[228:229], v[192:193]
	v_pk_fma_f32 v[196:197], v[68:69], v[232:233], v[196:197]
	v_pk_fma_f32 v[186:187], v[70:71], v[222:223], v[186:187]
	v_pk_fma_f32 v[190:191], v[70:71], v[226:227], v[190:191]
	v_pk_fma_f32 v[194:195], v[70:71], v[230:231], v[194:195]
	v_pk_fma_f32 v[198:199], v[70:71], v[234:235], v[198:199]
	ds_read_b128 v[220:223], v4 offset:240
	ds_read_b128 v[224:227], v4 offset:496
	ds_read_b128 v[228:231], v4 offset:752
	ds_read_b128 v[232:235], v4 offset:1008
	s_waitcnt lgkmcnt(4)
; #define LAS __attribute__((address_space(3)))
; __device__ __forceinline__ void rw_post(Frame& F) {
;     ...
;                     for (int q = 0; q < 4; ++q) { f32x4 a = (f32x4){0.f, 0.f, 0.f, 0.f};
; #pragma unroll
;                         for (int i = 0; i < 16; ++i) a = __builtin_elementwise_fma(Sr[i], *(const LAS f32x4*)(cs + q * 64 + 4 * i), a);
;                         y[4 * hf + q] += (a[0] + a[1]) + (a[2] + a[3]); }
;                     asm volatile("s_waitcnt lgkmcnt(0)" ::: "memory"); }
;             }
; #pragma unroll
;             for (int q = 0; q < 8; ++q) { const int row = rb0 + t0 + q;
;                 const float mean = wsum(y[q]) * (1.f / 64.f); const float dv = y[q] - mean; const float var = wsum(dv * dv) * (1.f / 64.f);
	v_pk_fma_f32 v[184:185], v[72:73], v[204:205], v[184:185]
	v_pk_fma_f32 v[188:189], v[72:73], v[208:209], v[188:189]
	v_pk_fma_f32 v[192:193], v[72:73], v[212:213], v[192:193]
	v_pk_fma_f32 v[196:197], v[72:73], v[216:217], v[196:197]
	v_pk_fma_f32 v[186:187], v[74:75], v[206:207], v[186:187]
	v_pk_fma_f32 v[190:191], v[74:75], v[210:211], v[190:191]
	v_pk_fma_f32 v[194:195], v[74:75], v[214:215], v[194:195]
	v_pk_fma_f32 v[198:199], v[74:75], v[218:219], v[198:199]
	s_waitcnt lgkmcnt(0)
	v_pk_fma_f32 v[184:185], v[76:77], v[220:221], v[184:185]
	v_pk_fma_f32 v[188:189], v[76:77], v[224:225], v[188:189]
	v_pk_fma_f32 v[192:193], v[76:77], v[228:229], v[192:193]
	v_pk_fma_f32 v[196:197], v[76:77], v[232:233], v[196:197]
	v_pk_fma_f32 v[186:187], v[78:79], v[222:223], v[186:187]
	v_pk_fma_f32 v[190:191], v[78:79], v[226:227], v[190:191]
	v_pk_fma_f32 v[194:195], v[78:79], v[230:231], v[194:195]
	v_pk_fma_f32 v[198:199], v[78:79], v[234:235], v[198:199]
	v_add_f32_e32 v184, v184, v185
	v_add_f32_e32 v188, v188, v189
	v_add_f32_e32 v192, v192, v193
	v_add_f32_e32 v196, v196, v197
	v_add_f32_e32 v186, v186, v187
	v_add_f32_e32 v190, v190, v191
	v_add_f32_e32 v194, v194, v195
	v_add_f32_e32 v198, v198, v199
	v_add_f32_e32 v184, v184, v186
	v_add_f32_e32 v188, v188, v190
	v_add_f32_e32 v192, v192, v194
	v_add_f32_e32 v196, v196, v198
	v_add_f32_e32 v100, v100, v184
	v_add_f32_e32 v105, v105, v188
	v_add_f32_e32 v110, v110, v192
	v_add_f32_e32 v115, v115, v196
.Lpo_nc2:
	v_add_f32_dpp v168, v100, v100 quad_perm:[1,0,3,2] row_mask:0xf bank_mask:0xf bound_ctrl:1
	v_add_f32_dpp v174, v105, v105 quad_perm:[1,0,3,2] row_mask:0xf bank_mask:0xf bound_ctrl:1
	v_add_f32_dpp v241, v110, v110 quad_perm:[1,0,3,2] row_mask:0xf bank_mask:0xf bound_ctrl:1
	v_add_f32_dpp v247, v115, v115 quad_perm:[1,0,3,2] row_mask:0xf bank_mask:0xf bound_ctrl:1
	v_add_f32_dpp v168, v168, v168 quad_perm:[2,3,0,1] row_mask:0xf bank_mask:0xf bound_ctrl:1
	v_add_f32_dpp v174, v174, v174 quad_perm:[2,3,0,1] row_mask:0xf bank_mask:0xf bound_ctrl:1
	v_add_f32_dpp v241, v241, v241 quad_perm:[2,3,0,1] row_mask:0xf bank_mask:0xf bound_ctrl:1
	v_add_f32_dpp v247, v247, v247 quad_perm:[2,3,0,1] row_mask:0xf bank_mask:0xf bound_ctrl:1
	v_add_f32_dpp v168, v168, v168 row_half_mirror row_mask:0xf bank_mask:0xf bound_ctrl:1
	v_add_f32_dpp v174, v174, v174 row_half_mirror row_mask:0xf bank_mask:0xf bound_ctrl:1
	v_add_f32_dpp v241, v241, v241 row_half_mirror row_mask:0xf bank_mask:0xf bound_ctrl:1
	v_add_f32_dpp v247, v247, v247 row_half_mirror row_mask:0xf bank_mask:0xf bound_ctrl:1
	v_add_f32_dpp v168, v168, v168 row_mirror row_mask:0xf bank_mask:0xf bound_ctrl:1
	v_add_f32_dpp v174, v174, v174 row_mirror row_mask:0xf bank_mask:0xf bound_ctrl:1
	v_add_f32_dpp v241, v241, v241 row_mirror row_mask:0xf bank_mask:0xf bound_ctrl:1
	v_add_f32_dpp v247, v247, v247 row_mirror row_mask:0xf bank_mask:0xf bound_ctrl:1
	v_readlane_b32 s36, v168, 16
	v_readlane_b32 s40, v174, 16
	v_readlane_b32 s44, v241, 16
	v_readlane_b32 s48, v247, 16
	v_readlane_b32 s37, v168, 48
	v_readlane_b32 s41, v174, 48
	v_readlane_b32 s45, v241, 48
	v_readlane_b32 s49, v247, 48
	v_readlane_b32 s38, v168, 0
	v_readlane_b32 s42, v174, 0
	v_readlane_b32 s46, v241, 0
	v_readlane_b32 s50, v247, 0
	v_readlane_b32 s39, v168, 32
	v_readlane_b32 s43, v174, 32
	v_readlane_b32 s47, v241, 32
	v_readlane_b32 s51, v247, 32
	v_mov_b32_e32 v168, s36
	v_mov_b32_e32 v174, s40
	v_mov_b32_e32 v241, s44
	v_mov_b32_e32 v247, s48
	v_mov_b32_e32 v169, s37
	v_mov_b32_e32 v175, s41
	v_mov_b32_e32 v242, s45
	v_mov_b32_e32 v248, s49
	v_add_f32_e32 v168, s38, v168
	v_add_f32_e32 v174, s42, v174
	v_add_f32_e32 v241, s46, v241
	v_add_f32_e32 v247, s50, v247
	v_add_f32_e32 v169, s39, v169
	v_add_f32_e32 v175, s43, v175
	v_add_f32_e32 v242, s47, v242
	v_add_f32_e32 v248, s51, v248
	v_add_f32_e32 v168, v168, v169
	v_add_f32_e32 v174, v174, v175
	v_add_f32_e32 v241, v241, v242
	v_add_f32_e32 v247, v247, v248
	v_fmamk_f32 v100, v168, 0xbc800000, v100
	v_fmamk_f32 v105, v174, 0xbc800000, v105
	v_fmamk_f32 v110, v241, 0xbc800000, v110
	v_fmamk_f32 v115, v247, 0xbc800000, v115
	v_mul_f32_e32 v168, v100, v100
	v_mul_f32_e32 v174, v105, v105
	v_mul_f32_e32 v241, v110, v110
	v_mul_f32_e32 v247, v115, v115
	v_mov_b32_dpp v168, v168 quad_perm:[1,0,3,2] row_mask:0xf bank_mask:0xf bound_ctrl:1
	v_mov_b32_dpp v174, v174 quad_perm:[1,0,3,2] row_mask:0xf bank_mask:0xf bound_ctrl:1
	v_mov_b32_dpp v241, v241 quad_perm:[1,0,3,2] row_mask:0xf bank_mask:0xf bound_ctrl:1
	v_mov_b32_dpp v247, v247 quad_perm:[1,0,3,2] row_mask:0xf bank_mask:0xf bound_ctrl:1
	v_fmac_f32_e32 v168, v100, v100
	v_fmac_f32_e32 v174, v105, v105
	v_fmac_f32_e32 v241, v110, v110
	v_fmac_f32_e32 v247, v115, v115
	v_add_f32_dpp v168, v168, v168 quad_perm:[2,3,0,1] row_mask:0xf bank_mask:0xf bound_ctrl:1
	v_add_f32_dpp v174, v174, v174 quad_perm:[2,3,0,1] row_mask:0xf bank_mask:0xf bound_ctrl:1
	v_add_f32_dpp v241, v241, v241 quad_perm:[2,3,0,1] row_mask:0xf bank_mask:0xf bound_ctrl:1
	v_add_f32_dpp v247, v247, v247 quad_perm:[2,3,0,1] row_mask:0xf bank_mask:0xf bound_ctrl:1
	v_add_f32_dpp v168, v168, v168 row_half_mirror row_mask:0xf bank_mask:0xf bound_ctrl:1
	v_add_f32_dpp v174, v174, v174 row_half_mirror row_mask:0xf bank_mask:0xf bound_ctrl:1
	v_add_f32_dpp v241, v241, v241 row_half_mirror row_mask:0xf bank_mask:0xf bound_ctrl:1
	v_add_f32_dpp v247, v247, v247 row_half_mirror row_mask:0xf bank_mask:0xf bound_ctrl:1
	v_add_f32_dpp v168, v168, v168 row_mirror row_mask:0xf bank_mask:0xf bound_ctrl:1
	v_add_f32_dpp v174, v174, v174 row_mirror row_mask:0xf bank_mask:0xf bound_ctrl:1
; __device__ __forceinline__ float bf2f(bf16 x) { return __uint_as_float(((unsigned)x) << 16); }
; __device__ __forceinline__ unsigned f2bf(float f) { return cvt_pk_bf16(f, 0.f) & 0xffffu; }
; __device__ __forceinline__ void rw_post(Frame& F) {
;     ...
;                 const float mean = wsum(y[q]) * (1.f / 64.f); const float dv = y[q] - mean; const float var = wsum(dv * dv) * (1.f / 64.f);
;                 const float yn = dv * (1.f / sqrtf(var + 64e-5f)) * g_ + b_;
;                 OB[(size_t)row * DH + col] = (bf16)f2bf((yn + rk[q] * vv[q]) * bf2f(gg[q])); }
	v_add_f32_dpp v241, v241, v241 row_mirror row_mask:0xf bank_mask:0xf bound_ctrl:1
	v_add_f32_dpp v247, v247, v247 row_mirror row_mask:0xf bank_mask:0xf bound_ctrl:1
	v_readlane_b32 s36, v168, 16
	v_readlane_b32 s40, v174, 16
	v_readlane_b32 s44, v241, 16
	v_readlane_b32 s48, v247, 16
	v_readlane_b32 s37, v168, 48
	v_readlane_b32 s41, v174, 48
	v_readlane_b32 s45, v241, 48
	v_readlane_b32 s49, v247, 48
	v_readlane_b32 s38, v168, 0
	v_readlane_b32 s42, v174, 0
	v_readlane_b32 s46, v241, 0
	v_readlane_b32 s50, v247, 0
	v_readlane_b32 s39, v168, 32
	v_readlane_b32 s43, v174, 32
	v_readlane_b32 s47, v241, 32
	v_readlane_b32 s51, v247, 32
	v_mov_b32_e32 v168, s36
	v_mov_b32_e32 v174, s40
	v_mov_b32_e32 v241, s44
	v_mov_b32_e32 v247, s48
	v_mov_b32_e32 v169, s37
	v_mov_b32_e32 v175, s41
	v_mov_b32_e32 v242, s45
	v_mov_b32_e32 v248, s49
	v_add_f32_e32 v168, s38, v168
	v_add_f32_e32 v174, s42, v174
	v_add_f32_e32 v241, s46, v241
	v_add_f32_e32 v247, s50, v247
	v_add_f32_e32 v169, s39, v169
	v_add_f32_e32 v175, s43, v175
	v_add_f32_e32 v242, s47, v242
	v_add_f32_e32 v248, s51, v248
	v_add_f32_e32 v168, v168, v169
	v_add_f32_e32 v174, v174, v175
	v_add_f32_e32 v241, v241, v242
	v_add_f32_e32 v247, v247, v248
	v_fmamk_f32 v168, v168, 0x3c800000, v9
	v_fmamk_f32 v174, v174, 0x3c800000, v9
	v_fmamk_f32 v241, v241, 0x3c800000, v9
	v_fmamk_f32 v247, v247, 0x3c800000, v9
	v_mul_f32_e32 v169, 0x4f800000, v168
	v_mul_f32_e32 v175, 0x4f800000, v174
	v_mul_f32_e32 v242, 0x4f800000, v241
	v_mul_f32_e32 v248, 0x4f800000, v247
	v_cmp_gt_f32_e64 s[52:53], s68, v168
	v_cmp_gt_f32_e64 s[54:55], s68, v174
	v_cmp_gt_f32_e64 s[56:57], s68, v241
	v_cmp_gt_f32_e64 s[58:59], s68, v247
	v_mov_b32_e32 v170, v168
	v_mov_b32_e32 v176, v174
	v_mov_b32_e32 v243, v241
	v_mov_b32_e32 v249, v247
	v_cndmask_b32_e64 v168, v170, v169, s[52:53]
	v_cndmask_b32_e64 v174, v176, v175, s[54:55]
	v_cndmask_b32_e64 v241, v243, v242, s[56:57]
	v_cndmask_b32_e64 v247, v249, v248, s[58:59]
	v_sqrt_f32_e32 v169, v168
	v_sqrt_f32_e32 v175, v174
	v_sqrt_f32_e32 v242, v241
	v_sqrt_f32_e32 v248, v247
	v_add_u32_e32 v170, -1, v169
	v_add_u32_e32 v176, -1, v175
	v_add_u32_e32 v243, -1, v242
	v_add_u32_e32 v249, -1, v248
	v_fma_f32 v171, -v170, v169, v168
	v_fma_f32 v177, -v176, v175, v174
	v_fma_f32 v244, -v243, v242, v241
	v_fma_f32 v250, -v249, v248, v247
	v_cmp_ge_f32_e64 s[60:61], 0, v171
	v_cmp_ge_f32_e64 s[62:63], 0, v177
	v_cmp_ge_f32_e64 s[64:65], 0, v244
	v_cmp_ge_f32_e64 s[66:67], 0, v250
	v_add_u32_e32 v171, 1, v169
	v_add_u32_e32 v177, 1, v175
	v_add_u32_e32 v244, 1, v242
	v_add_u32_e32 v250, 1, v248
	v_cndmask_b32_e64 v170, v169, v170, s[60:61]
	v_cndmask_b32_e64 v176, v175, v176, s[62:63]
	v_cndmask_b32_e64 v243, v242, v243, s[64:65]
	v_cndmask_b32_e64 v249, v248, v249, s[66:67]
	v_fma_f32 v169, -v171, v169, v168
	v_fma_f32 v175, -v177, v175, v174
	v_fma_f32 v242, -v244, v242, v241
	v_fma_f32 v248, -v250, v248, v247
	v_cmp_lt_f32_e64 s[60:61], 0, v169
	v_cmp_lt_f32_e64 s[62:63], 0, v175
	v_cmp_lt_f32_e64 s[64:65], 0, v242
	v_cmp_lt_f32_e64 s[66:67], 0, v248
	v_cndmask_b32_e64 v169, v170, v171, s[60:61]
	v_cndmask_b32_e64 v175, v176, v177, s[62:63]
	v_cndmask_b32_e64 v242, v243, v244, s[64:65]
	v_cndmask_b32_e64 v248, v249, v250, s[66:67]
	v_mul_f32_e32 v170, 0x37800000, v169
	v_mul_f32_e32 v176, 0x37800000, v175
	v_mul_f32_e32 v243, 0x37800000, v242
	v_mul_f32_e32 v249, 0x37800000, v248
	v_cndmask_b32_e64 v169, v169, v170, s[52:53]
	v_cndmask_b32_e64 v175, v175, v176, s[54:55]
	v_cndmask_b32_e64 v242, v242, v243, s[56:57]
	v_cndmask_b32_e64 v248, v248, v249, s[58:59]
	v_cmp_class_f32_e64 s[60:61], v168, v8
	v_cmp_class_f32_e64 s[62:63], v174, v8
	v_cmp_class_f32_e64 s[64:65], v241, v8
	v_cmp_class_f32_e64 s[66:67], v247, v8
	v_cndmask_b32_e64 v168, v169, v168, s[60:61]
	v_cndmask_b32_e64 v174, v175, v174, s[62:63]
	v_cndmask_b32_e64 v241, v242, v241, s[64:65]
	v_cndmask_b32_e64 v247, v248, v247, s[66:67]
	v_div_scale_f32 v169, s[60:61], v168, v168, 1.0
	v_rcp_f32_e32 v170, v169
	s_nop 0
	v_fma_f32 v171, -v169, v170, 1.0
	v_fmac_f32_e32 v170, v171, v170
	v_div_scale_f32 v171, vcc, 1.0, v168, 1.0
	v_mul_f32_e32 v172, v171, v170
	v_fma_f32 v173, -v169, v172, v171
	v_fmac_f32_e32 v172, v173, v170
	v_fma_f32 v169, -v169, v172, v171
	v_div_fmas_f32 v169, v169, v170, v172
	v_div_fixup_f32 v168, v169, v168, 1.0
	v_div_scale_f32 v175, s[62:63], v174, v174, 1.0
	v_rcp_f32_e32 v176, v175
	s_nop 0
	v_fma_f32 v177, -v175, v176, 1.0
	v_fmac_f32_e32 v176, v177, v176
	v_div_scale_f32 v177, vcc, 1.0, v174, 1.0
	v_mul_f32_e32 v236, v177, v176
	v_fma_f32 v237, -v175, v236, v177
	v_fmac_f32_e32 v236, v237, v176
	v_fma_f32 v175, -v175, v236, v177
	v_div_fmas_f32 v175, v175, v176, v236
	v_div_fixup_f32 v174, v175, v174, 1.0
	v_div_scale_f32 v242, s[64:65], v241, v241, 1.0
	v_rcp_f32_e32 v243, v242
	s_nop 0
	v_fma_f32 v244, -v242, v243, 1.0
	v_fmac_f32_e32 v243, v244, v243
	v_div_scale_f32 v244, vcc, 1.0, v241, 1.0
	v_mul_f32_e32 v245, v244, v243
	v_fma_f32 v246, -v242, v245, v244
	v_fmac_f32_e32 v245, v246, v243
	v_fma_f32 v242, -v242, v245, v244
	v_div_fmas_f32 v242, v242, v243, v245
	v_div_fixup_f32 v241, v242, v241, 1.0
	v_div_scale_f32 v248, s[66:67], v247, v247, 1.0
	v_rcp_f32_e32 v249, v248
	s_nop 0
	v_fma_f32 v250, -v248, v249, 1.0
	v_fmac_f32_e32 v249, v250, v249
	v_div_scale_f32 v250, vcc, 1.0, v247, 1.0
	v_mul_f32_e32 v251, v250, v249
	v_fma_f32 v252, -v248, v251, v250
	v_fmac_f32_e32 v251, v252, v249
	v_fma_f32 v248, -v248, v251, v250
	v_div_fmas_f32 v248, v248, v249, v251
	v_div_fixup_f32 v247, v248, v247, 1.0
	v_mul_f32_e32 v100, v100, v168
	v_mul_f32_e32 v105, v105, v174
	v_mul_f32_e32 v110, v110, v241
	v_mul_f32_e32 v115, v115, v247
	v_lshlrev_b32_e32 v103, 16, v103
	v_lshlrev_b32_e32 v108, 16, v108
	v_lshlrev_b32_e32 v113, 16, v113
	v_lshlrev_b32_e32 v118, 16, v118
	v_fma_f32 v100, v6, v100, v7
	v_fma_f32 v105, v6, v105, v7
	v_fma_f32 v110, v6, v110, v7
	v_fma_f32 v115, v6, v115, v7
	v_fmac_f32_e32 v100, s73, v101
	v_fmac_f32_e32 v105, s26, v106
	v_fmac_f32_e32 v110, s27, v111
	v_fmac_f32_e32 v115, s32, v116
	v_mul_f32_e32 v100, v100, v103
	v_mul_f32_e32 v105, v105, v108
	v_mul_f32_e32 v110, v110, v113
	v_mul_f32_e32 v115, v115, v118
	v_cvt_pk_bf16_f32 v169, v100, v100
	v_cvt_pk_bf16_f32 v175, v105, v105
	v_cvt_pk_bf16_f32 v242, v110, v110
	v_cvt_pk_bf16_f32 v248, v115, v115
	global_store_short v2, v169, s[28:29]
	s_add_u32 s28, s28, 0x1000
	s_addc_u32 s29, s29, 0
	global_store_short v2, v175, s[28:29]
	s_add_u32 s28, s28, 0x1000
	s_addc_u32 s29, s29, 0
	global_store_short v2, v242, s[28:29]
	s_add_u32 s28, s28, 0x1000
	s_addc_u32 s29, s29, 0
	global_store_short v2, v248, s[28:29]
	s_add_u32 s28, s28, 0x1000
	s_addc_u32 s29, s29, 0
	s_waitcnt vmcnt(8)
; #define LAS __attribute__((address_space(3)))
; #define POST_LD(Y_, V_, G_, R_, C_, t) do { _Pragma("unroll") for (int q = 0; q < 8; ++q) { const size_t o_ = (size_t)((t) + q) * DH; Y_[q] = yp[o_]; V_[q] = vp[o_]; G_[q] = gp[o_]; R_[q] = rp[((t) + q) * 32]; C_[q] = cp[o_]; } } while (0)
; __device__ __forceinline__ void rw_post(Frame& F) {
;     ...
;         POST_LD(y, vv, gg, rk, cc, 0);
;         for (int t0 = 0; t0 < 64; t0 += 8) {
;             float ny[8], nv[8], nr[8], nc[8]; bf16 ng[8];
;             const int tn = t0 + 8 < 64 ? t0 + 8 : t0;
;             POST_LD(ny, nv, ng, nr, nc, tn);
;             if (k > 0) {
;                 LAS float* cs = (LAS float*)(F.lds + 131072 + F.wave * 1024);
; #pragma unroll
;                 for (int hf = 0; hf < 2; ++hf) {
; #pragma unroll
;                     for (int q = 0; q < 4; ++q) cs[q * 64 + lane] = cc[4 * hf + q];
;                     asm volatile("s_waitcnt lgkmcnt(0)" ::: "memory");
; #pragma unroll
;                     for (int q = 0; q < 4; ++q) { f32x4 a = (f32x4){0.f, 0.f, 0.f, 0.f};
; #pragma unroll
;                         for (int i = 0; i < 16; ++i) a = __builtin_elementwise_fma(Sr[i], *(const LAS f32x4*)(cs + q * 64 + 4 * i), a);
;                         y[4 * hf + q] += (a[0] + a[1]) + (a[2] + a[3]); }
	ds_write_b128 v13, v[120:123] offset:0
	ds_write_b128 v13, v[124:127] offset:1024
	ds_write_b128 v13, v[128:131] offset:16384
	ds_write_b128 v13, v[132:135] offset:17408
	ds_write_b128 v13, v[136:139] offset:32768
	ds_write_b128 v13, v[140:143] offset:33792
	ds_write_b128 v15, v[144:147]
	v_readlane_b32 s69, v148, 0
	v_readlane_b32 s70, v148, 1
	v_readlane_b32 s71, v148, 2
	v_readlane_b32 s72, v148, 3
	v_readlane_b32 s73, v148, 4
	v_readlane_b32 s26, v148, 5
	v_readlane_b32 s27, v148, 6
	v_readlane_b32 s32, v148, 7
	s_cmp_eq_u32 s25, 1
	s_cbranch_scc1 .Lpo_nopf
	global_load_dwordx4 v[120:123], v11, s[6:7]
	global_load_dwordx4 v[124:127], v11, s[6:7] offset:1024
	global_load_dwordx4 v[128:131], v11, s[8:9]
	global_load_dwordx4 v[132:135], v11, s[8:9] offset:1024
	global_load_dwordx4 v[136:139], v11, s[14:15]
	global_load_dwordx4 v[140:143], v11, s[14:15] offset:1024
	global_load_dwordx4 v[144:147], v11, s[10:11]
	global_load_dword v148, v153, s[12:13]
	s_add_u32 s6, s6, 0x10000
	s_addc_u32 s7, s7, 0
	s_add_u32 s8, s8, 0x10000
	s_addc_u32 s9, s9, 0
	s_add_u32 s14, s14, 0x10000
	s_addc_u32 s15, s15, 0
	s_add_u32 s10, s10, 0x8000
	s_addc_u32 s11, s11, 0
	s_add_u32 s12, s12, 0x400
	s_addc_u32 s13, s13, 0
.Lpo_nopf:
	s_waitcnt lgkmcnt(0)
	s_barrier
	ds_read_b32 v80, v150 offset:0
	ds_read_b32 v81, v150 offset:16384
	ds_read_b32 v82, v150 offset:32768
	ds_read_u16 v83, v152 offset:0
	ds_read_b32 v85, v150 offset:2048
	ds_read_b32 v86, v150 offset:18432
	ds_read_b32 v87, v150 offset:34816
	ds_read_u16 v88, v152 offset:1024
	ds_read_b32 v90, v150 offset:4096
	ds_read_b32 v91, v150 offset:20480
	ds_read_b32 v92, v150 offset:36864
	ds_read_u16 v93, v152 offset:2048
	ds_read_b32 v95, v150 offset:6144
	ds_read_b32 v96, v150 offset:22528
	ds_read_b32 v97, v150 offset:38912
	ds_read_u16 v98, v152 offset:3072
	ds_read_b32 v100, v150 offset:8192
	ds_read_b32 v101, v150 offset:24576
	ds_read_b32 v102, v150 offset:40960
	ds_read_u16 v103, v152 offset:4096
	ds_read_b32 v105, v150 offset:10240
	ds_read_b32 v106, v150 offset:26624
	ds_read_b32 v107, v150 offset:43008
	ds_read_u16 v108, v152 offset:5120
	ds_read_b32 v110, v150 offset:12288
	ds_read_b32 v111, v150 offset:28672
	ds_read_b32 v112, v150 offset:45056
	ds_read_u16 v113, v152 offset:6144
	ds_read_b32 v115, v150 offset:14336
	ds_read_b32 v116, v150 offset:30720
	ds_read_b32 v117, v150 offset:47104
	ds_read_u16 v118, v152 offset:7168
	s_waitcnt lgkmcnt(0)
	s_cmp_eq_u32 s23, 0
	s_cbranch_scc1 .Lpo_nc3
	ds_write_b32 v3, v82
	ds_write_b32 v3, v87 offset:256
	ds_write_b32 v3, v92 offset:512
	ds_write_b32 v3, v97 offset:768
	s_waitcnt lgkmcnt(0)
	ds_read_b128 v[204:207], v4 offset:0
	ds_read_b128 v[208:211], v4 offset:256
	ds_read_b128 v[212:215], v4 offset:512
	ds_read_b128 v[216:219], v4 offset:768
	ds_read_b128 v[220:223], v4 offset:16
	ds_read_b128 v[224:227], v4 offset:272
	ds_read_b128 v[228:231], v4 offset:528
	ds_read_b128 v[232:235], v4 offset:784
	s_waitcnt lgkmcnt(4)
	v_pk_mul_f32 v[184:185], v[16:17], v[204:205]
	v_pk_mul_f32 v[188:189], v[16:17], v[208:209]
	v_pk_mul_f32 v[192:193], v[16:17], v[212:213]
	v_pk_mul_f32 v[196:197], v[16:17], v[216:217]
	v_pk_mul_f32 v[186:187], v[18:19], v[206:207]
	v_pk_mul_f32 v[190:191], v[18:19], v[210:211]
	v_pk_mul_f32 v[194:195], v[18:19], v[214:215]
	v_pk_mul_f32 v[198:199], v[18:19], v[218:219]
	ds_read_b128 v[204:207], v4 offset:32
	ds_read_b128 v[208:211], v4 offset:288
	ds_read_b128 v[212:215], v4 offset:544
	ds_read_b128 v[216:219], v4 offset:800
	s_waitcnt lgkmcnt(4)
	v_pk_fma_f32 v[184:185], v[20:21], v[220:221], v[184:185]
	v_pk_fma_f32 v[188:189], v[20:21], v[224:225], v[188:189]
	v_pk_fma_f32 v[192:193], v[20:21], v[228:229], v[192:193]
	v_pk_fma_f32 v[196:197], v[20:21], v[232:233], v[196:197]
	v_pk_fma_f32 v[186:187], v[22:23], v[222:223], v[186:187]
	v_pk_fma_f32 v[190:191], v[22:23], v[226:227], v[190:191]
	v_pk_fma_f32 v[194:195], v[22:23], v[230:231], v[194:195]
	v_pk_fma_f32 v[198:199], v[22:23], v[234:235], v[198:199]
	ds_read_b128 v[220:223], v4 offset:48
	ds_read_b128 v[224:227], v4 offset:304
	ds_read_b128 v[228:231], v4 offset:560
	ds_read_b128 v[232:235], v4 offset:816
	s_waitcnt lgkmcnt(4)
	v_pk_fma_f32 v[184:185], v[24:25], v[204:205], v[184:185]
	v_pk_fma_f32 v[188:189], v[24:25], v[208:209], v[188:189]
	v_pk_fma_f32 v[192:193], v[24:25], v[212:213], v[192:193]
	v_pk_fma_f32 v[196:197], v[24:25], v[216:217], v[196:197]
	v_pk_fma_f32 v[186:187], v[26:27], v[206:207], v[186:187]
	v_pk_fma_f32 v[190:191], v[26:27], v[210:211], v[190:191]
	v_pk_fma_f32 v[194:195], v[26:27], v[214:215], v[194:195]
	v_pk_fma_f32 v[198:199], v[26:27], v[218:219], v[198:199]
	ds_read_b128 v[204:207], v4 offset:64
	ds_read_b128 v[208:211], v4 offset:320
	ds_read_b128 v[212:215], v4 offset:576
	ds_read_b128 v[216:219], v4 offset:832
	s_waitcnt lgkmcnt(4)
	v_pk_fma_f32 v[184:185], v[28:29], v[220:221], v[184:185]
	v_pk_fma_f32 v[188:189], v[28:29], v[224:225], v[188:189]
	v_pk_fma_f32 v[192:193], v[28:29], v[228:229], v[192:193]
	v_pk_fma_f32 v[196:197], v[28:29], v[232:233], v[196:197]
	v_pk_fma_f32 v[186:187], v[30:31], v[222:223], v[186:187]
	v_pk_fma_f32 v[190:191], v[30:31], v[226:227], v[190:191]
	v_pk_fma_f32 v[194:195], v[30:31], v[230:231], v[194:195]
	v_pk_fma_f32 v[198:199], v[30:31], v[234:235], v[198:199]
	ds_read_b128 v[220:223], v4 offset:80
	ds_read_b128 v[224:227], v4 offset:336
	ds_read_b128 v[228:231], v4 offset:592
	ds_read_b128 v[232:235], v4 offset:848
	s_waitcnt lgkmcnt(4)
; #define LAS __attribute__((address_space(3)))
; __device__ __forceinline__ void rw_post(Frame& F) {
;     ...
;                     for (int q = 0; q < 4; ++q) { f32x4 a = (f32x4){0.f, 0.f, 0.f, 0.f};
; #pragma unroll
;                         for (int i = 0; i < 16; ++i) a = __builtin_elementwise_fma(Sr[i], *(const LAS f32x4*)(cs + q * 64 + 4 * i), a);
;                         y[4 * hf + q] += (a[0] + a[1]) + (a[2] + a[3]); }
	v_pk_fma_f32 v[184:185], v[32:33], v[204:205], v[184:185]
	v_pk_fma_f32 v[188:189], v[32:33], v[208:209], v[188:189]
	v_pk_fma_f32 v[192:193], v[32:33], v[212:213], v[192:193]
	v_pk_fma_f32 v[196:197], v[32:33], v[216:217], v[196:197]
	v_pk_fma_f32 v[186:187], v[34:35], v[206:207], v[186:187]
	v_pk_fma_f32 v[190:191], v[34:35], v[210:211], v[190:191]
	v_pk_fma_f32 v[194:195], v[34:35], v[214:215], v[194:195]
	v_pk_fma_f32 v[198:199], v[34:35], v[218:219], v[198:199]
	ds_read_b128 v[204:207], v4 offset:96
	ds_read_b128 v[208:211], v4 offset:352
	ds_read_b128 v[212:215], v4 offset:608
	ds_read_b128 v[216:219], v4 offset:864
	s_waitcnt lgkmcnt(4)
	v_pk_fma_f32 v[184:185], v[36:37], v[220:221], v[184:185]
	v_pk_fma_f32 v[188:189], v[36:37], v[224:225], v[188:189]
	v_pk_fma_f32 v[192:193], v[36:37], v[228:229], v[192:193]
	v_pk_fma_f32 v[196:197], v[36:37], v[232:233], v[196:197]
	v_pk_fma_f32 v[186:187], v[38:39], v[222:223], v[186:187]
	v_pk_fma_f32 v[190:191], v[38:39], v[226:227], v[190:191]
	v_pk_fma_f32 v[194:195], v[38:39], v[230:231], v[194:195]
	v_pk_fma_f32 v[198:199], v[38:39], v[234:235], v[198:199]
	ds_read_b128 v[220:223], v4 offset:112
	ds_read_b128 v[224:227], v4 offset:368
	ds_read_b128 v[228:231], v4 offset:624
	ds_read_b128 v[232:235], v4 offset:880
	s_waitcnt lgkmcnt(4)
	v_pk_fma_f32 v[184:185], v[40:41], v[204:205], v[184:185]
	v_pk_fma_f32 v[188:189], v[40:41], v[208:209], v[188:189]
	v_pk_fma_f32 v[192:193], v[40:41], v[212:213], v[192:193]
	v_pk_fma_f32 v[196:197], v[40:41], v[216:217], v[196:197]
	v_pk_fma_f32 v[186:187], v[42:43], v[206:207], v[186:187]
	v_pk_fma_f32 v[190:191], v[42:43], v[210:211], v[190:191]
	v_pk_fma_f32 v[194:195], v[42:43], v[214:215], v[194:195]
	v_pk_fma_f32 v[198:199], v[42:43], v[218:219], v[198:199]
	ds_read_b128 v[204:207], v4 offset:128
	ds_read_b128 v[208:211], v4 offset:384
	ds_read_b128 v[212:215], v4 offset:640
	ds_read_b128 v[216:219], v4 offset:896
	s_waitcnt lgkmcnt(4)
	v_pk_fma_f32 v[184:185], v[44:45], v[220:221], v[184:185]
	v_pk_fma_f32 v[188:189], v[44:45], v[224:225], v[188:189]
	v_pk_fma_f32 v[192:193], v[44:45], v[228:229], v[192:193]
	v_pk_fma_f32 v[196:197], v[44:45], v[232:233], v[196:197]
	v_pk_fma_f32 v[186:187], v[46:47], v[222:223], v[186:187]
	v_pk_fma_f32 v[190:191], v[46:47], v[226:227], v[190:191]
	v_pk_fma_f32 v[194:195], v[46:47], v[230:231], v[194:195]
	v_pk_fma_f32 v[198:199], v[46:47], v[234:235], v[198:199]
	ds_read_b128 v[220:223], v4 offset:144
	ds_read_b128 v[224:227], v4 offset:400
	ds_read_b128 v[228:231], v4 offset:656
	ds_read_b128 v[232:235], v4 offset:912
	s_waitcnt lgkmcnt(4)
	v_pk_fma_f32 v[184:185], v[48:49], v[204:205], v[184:185]
	v_pk_fma_f32 v[188:189], v[48:49], v[208:209], v[188:189]
	v_pk_fma_f32 v[192:193], v[48:49], v[212:213], v[192:193]
	v_pk_fma_f32 v[196:197], v[48:49], v[216:217], v[196:197]
	v_pk_fma_f32 v[186:187], v[50:51], v[206:207], v[186:187]
	v_pk_fma_f32 v[190:191], v[50:51], v[210:211], v[190:191]
	v_pk_fma_f32 v[194:195], v[50:51], v[214:215], v[194:195]
	v_pk_fma_f32 v[198:199], v[50:51], v[218:219], v[198:199]
	ds_read_b128 v[204:207], v4 offset:160
	ds_read_b128 v[208:211], v4 offset:416
	ds_read_b128 v[212:215], v4 offset:672
	ds_read_b128 v[216:219], v4 offset:928
	s_waitcnt lgkmcnt(4)
	v_pk_fma_f32 v[184:185], v[52:53], v[220:221], v[184:185]
	v_pk_fma_f32 v[188:189], v[52:53], v[224:225], v[188:189]
	v_pk_fma_f32 v[192:193], v[52:53], v[228:229], v[192:193]
	v_pk_fma_f32 v[196:197], v[52:53], v[232:233], v[196:197]
	v_pk_fma_f32 v[186:187], v[54:55], v[222:223], v[186:187]
	v_pk_fma_f32 v[190:191], v[54:55], v[226:227], v[190:191]
	v_pk_fma_f32 v[194:195], v[54:55], v[230:231], v[194:195]
	v_pk_fma_f32 v[198:199], v[54:55], v[234:235], v[198:199]
	ds_read_b128 v[220:223], v4 offset:176
	ds_read_b128 v[224:227], v4 offset:432
	ds_read_b128 v[228:231], v4 offset:688
	ds_read_b128 v[232:235], v4 offset:944
	s_waitcnt lgkmcnt(4)
; #define LAS __attribute__((address_space(3)))
; __device__ __forceinline__ void rw_post(Frame& F) {
;     ...
;                     for (int q = 0; q < 4; ++q) { f32x4 a = (f32x4){0.f, 0.f, 0.f, 0.f};
; #pragma unroll
;                         for (int i = 0; i < 16; ++i) a = __builtin_elementwise_fma(Sr[i], *(const LAS f32x4*)(cs + q * 64 + 4 * i), a);
;                         y[4 * hf + q] += (a[0] + a[1]) + (a[2] + a[3]); }
	v_pk_fma_f32 v[184:185], v[56:57], v[204:205], v[184:185]
	v_pk_fma_f32 v[188:189], v[56:57], v[208:209], v[188:189]
	v_pk_fma_f32 v[192:193], v[56:57], v[212:213], v[192:193]
	v_pk_fma_f32 v[196:197], v[56:57], v[216:217], v[196:197]
	v_pk_fma_f32 v[186:187], v[58:59], v[206:207], v[186:187]
	v_pk_fma_f32 v[190:191], v[58:59], v[210:211], v[190:191]
	v_pk_fma_f32 v[194:195], v[58:59], v[214:215], v[194:195]
	v_pk_fma_f32 v[198:199], v[58:59], v[218:219], v[198:199]
	ds_read_b128 v[204:207], v4 offset:192
	ds_read_b128 v[208:211], v4 offset:448
	ds_read_b128 v[212:215], v4 offset:704
	ds_read_b128 v[216:219], v4 offset:960
	s_waitcnt lgkmcnt(4)
	v_pk_fma_f32 v[184:185], v[60:61], v[220:221], v[184:185]
	v_pk_fma_f32 v[188:189], v[60:61], v[224:225], v[188:189]
	v_pk_fma_f32 v[192:193], v[60:61], v[228:229], v[192:193]
	v_pk_fma_f32 v[196:197], v[60:61], v[232:233], v[196:197]
	v_pk_fma_f32 v[186:187], v[62:63], v[222:223], v[186:187]
	v_pk_fma_f32 v[190:191], v[62:63], v[226:227], v[190:191]
	v_pk_fma_f32 v[194:195], v[62:63], v[230:231], v[194:195]
	v_pk_fma_f32 v[198:199], v[62:63], v[234:235], v[198:199]
	ds_read_b128 v[220:223], v4 offset:208
	ds_read_b128 v[224:227], v4 offset:464
	ds_read_b128 v[228:231], v4 offset:720
	ds_read_b128 v[232:235], v4 offset:976
	s_waitcnt lgkmcnt(4)
	v_pk_fma_f32 v[184:185], v[64:65], v[204:205], v[184:185]
	v_pk_fma_f32 v[188:189], v[64:65], v[208:209], v[188:189]
	v_pk_fma_f32 v[192:193], v[64:65], v[212:213], v[192:193]
	v_pk_fma_f32 v[196:197], v[64:65], v[216:217], v[196:197]
	v_pk_fma_f32 v[186:187], v[66:67], v[206:207], v[186:187]
	v_pk_fma_f32 v[190:191], v[66:67], v[210:211], v[190:191]
	v_pk_fma_f32 v[194:195], v[66:67], v[214:215], v[194:195]
	v_pk_fma_f32 v[198:199], v[66:67], v[218:219], v[198:199]
	ds_read_b128 v[204:207], v4 offset:224
	ds_read_b128 v[208:211], v4 offset:480
	ds_read_b128 v[212:215], v4 offset:736
	ds_read_b128 v[216:219], v4 offset:992
	s_waitcnt lgkmcnt(4)
	v_pk_fma_f32 v[184:185], v[68:69], v[220:221], v[184:185]
	v_pk_fma_f32 v[188:189], v[68:69], v[224:225], v[188:189]
	v_pk_fma_f32 v[192:193], v[68:69], v[228:229], v[192:193]
	v_pk_fma_f32 v[196:197], v[68:69], v[232:233], v[196:197]
	v_pk_fma_f32 v[186:187], v[70:71], v[222:223], v[186:187]
	v_pk_fma_f32 v[190:191], v[70:71], v[226:227], v[190:191]
	v_pk_fma_f32 v[194:195], v[70:71], v[230:231], v[194:195]
	v_pk_fma_f32 v[198:199], v[70:71], v[234:235], v[198:199]
	ds_read_b128 v[220:223], v4 offset:240
	ds_read_b128 v[224:227], v4 offset:496
	ds_read_b128 v[228:231], v4 offset:752
	ds_read_b128 v[232:235], v4 offset:1008
	s_waitcnt lgkmcnt(4)
	v_pk_fma_f32 v[184:185], v[72:73], v[204:205], v[184:185]
	v_pk_fma_f32 v[188:189], v[72:73], v[208:209], v[188:189]
	v_pk_fma_f32 v[192:193], v[72:73], v[212:213], v[192:193]
	v_pk_fma_f32 v[196:197], v[72:73], v[216:217], v[196:197]
	v_pk_fma_f32 v[186:187], v[74:75], v[206:207], v[186:187]
	v_pk_fma_f32 v[190:191], v[74:75], v[210:211], v[190:191]
	v_pk_fma_f32 v[194:195], v[74:75], v[214:215], v[194:195]
	v_pk_fma_f32 v[198:199], v[74:75], v[218:219], v[198:199]
	s_waitcnt lgkmcnt(0)
	v_pk_fma_f32 v[184:185], v[76:77], v[220:221], v[184:185]
	v_pk_fma_f32 v[188:189], v[76:77], v[224:225], v[188:189]
	v_pk_fma_f32 v[192:193], v[76:77], v[228:229], v[192:193]
	v_pk_fma_f32 v[196:197], v[76:77], v[232:233], v[196:197]
	v_pk_fma_f32 v[186:187], v[78:79], v[222:223], v[186:187]
	v_pk_fma_f32 v[190:191], v[78:79], v[226:227], v[190:191]
	v_pk_fma_f32 v[194:195], v[78:79], v[230:231], v[194:195]
	v_pk_fma_f32 v[198:199], v[78:79], v[234:235], v[198:199]
	v_add_f32_e32 v184, v184, v185
	v_add_f32_e32 v188, v188, v189
	v_add_f32_e32 v192, v192, v193
	v_add_f32_e32 v196, v196, v197
	v_add_f32_e32 v186, v186, v187
	v_add_f32_e32 v190, v190, v191
	v_add_f32_e32 v194, v194, v195
	v_add_f32_e32 v198, v198, v199
	v_add_f32_e32 v184, v184, v186
	v_add_f32_e32 v188, v188, v190
	v_add_f32_e32 v192, v192, v194
	v_add_f32_e32 v196, v196, v198
	v_add_f32_e32 v80, v80, v184
	v_add_f32_e32 v85, v85, v188
	v_add_f32_e32 v90, v90, v192
	v_add_f32_e32 v95, v95, v196

; __device__ __forceinline__ float dpp_xor1(float x) { return __builtin_bit_cast(float, __builtin_amdgcn_update_dpp(0, __builtin_bit_cast(int, x), 0xB1, 0xF, 0xF, true)); }
; __device__ __forceinline__ float dpp_xor2(float x) { return __builtin_bit_cast(float, __builtin_amdgcn_update_dpp(0, __builtin_bit_cast(int, x), 0x4E, 0xF, 0xF, true)); }
; __device__ __forceinline__ float dpp_hmir(float x) { return __builtin_bit_cast(float, __builtin_amdgcn_update_dpp(0, __builtin_bit_cast(int, x), 0x141, 0xF, 0xF, true)); }
; __device__ __forceinline__ float dpp_mir(float x)  { return __builtin_bit_cast(float, __builtin_amdgcn_update_dpp(0, __builtin_bit_cast(int, x), 0x140, 0xF, 0xF, true)); }
; __device__ __forceinline__ float red16(float x) { x += dpp_xor1(x); x += dpp_xor2(x); x += dpp_hmir(x); x += dpp_mir(x); return x; }
; __device__ __forceinline__ float wsum(float x) {
;     x = red16(x); const int xi = __builtin_bit_cast(int, x);
;     const float r0 = __builtin_bit_cast(float, __builtin_amdgcn_readlane(xi, 0)), r1 = __builtin_bit_cast(float, __builtin_amdgcn_readlane(xi, 16));
;     const float r2 = __builtin_bit_cast(float, __builtin_amdgcn_readlane(xi, 32)), r3 = __builtin_bit_cast(float, __builtin_amdgcn_readlane(xi, 48));
;     return (r0 + r1) + (r2 + r3);
; __device__ __forceinline__ void rw_post(Frame& F) {
;     ...
;             for (int q = 0; q < 8; ++q) { const int row = rb0 + t0 + q;
;                 const float mean = wsum(y[q]) * (1.f / 64.f); const float dv = y[q] - mean; const float var = wsum(dv * dv) * (1.f / 64.f);
;                 const float yn = dv * (1.f / sqrtf(var + 64e-5f)) * g_ + b_;
.Lpo_nc4:
	v_add_f32_dpp v168, v100, v100 quad_perm:[1,0,3,2] row_mask:0xf bank_mask:0xf bound_ctrl:1
	v_add_f32_dpp v174, v105, v105 quad_perm:[1,0,3,2] row_mask:0xf bank_mask:0xf bound_ctrl:1
	v_add_f32_dpp v241, v110, v110 quad_perm:[1,0,3,2] row_mask:0xf bank_mask:0xf bound_ctrl:1
	v_add_f32_dpp v247, v115, v115 quad_perm:[1,0,3,2] row_mask:0xf bank_mask:0xf bound_ctrl:1
	v_add_f32_dpp v168, v168, v168 quad_perm:[2,3,0,1] row_mask:0xf bank_mask:0xf bound_ctrl:1
	v_add_f32_dpp v174, v174, v174 quad_perm:[2,3,0,1] row_mask:0xf bank_mask:0xf bound_ctrl:1
	v_add_f32_dpp v241, v241, v241 quad_perm:[2,3,0,1] row_mask:0xf bank_mask:0xf bound_ctrl:1
	v_add_f32_dpp v247, v247, v247 quad_perm:[2,3,0,1] row_mask:0xf bank_mask:0xf bound_ctrl:1
	v_add_f32_dpp v168, v168, v168 row_half_mirror row_mask:0xf bank_mask:0xf bound_ctrl:1
	v_add_f32_dpp v174, v174, v174 row_half_mirror row_mask:0xf bank_mask:0xf bound_ctrl:1
	v_add_f32_dpp v241, v241, v241 row_half_mirror row_mask:0xf bank_mask:0xf bound_ctrl:1
	v_add_f32_dpp v247, v247, v247 row_half_mirror row_mask:0xf bank_mask:0xf bound_ctrl:1
	v_add_f32_dpp v168, v168, v168 row_mirror row_mask:0xf bank_mask:0xf bound_ctrl:1
	v_add_f32_dpp v174, v174, v174 row_mirror row_mask:0xf bank_mask:0xf bound_ctrl:1
	v_add_f32_dpp v241, v241, v241 row_mirror row_mask:0xf bank_mask:0xf bound_ctrl:1
	v_add_f32_dpp v247, v247, v247 row_mirror row_mask:0xf bank_mask:0xf bound_ctrl:1
	v_readlane_b32 s36, v168, 16
	v_readlane_b32 s40, v174, 16
	v_readlane_b32 s44, v241, 16
	v_readlane_b32 s48, v247, 16
	v_readlane_b32 s37, v168, 48
	v_readlane_b32 s41, v174, 48
	v_readlane_b32 s45, v241, 48
	v_readlane_b32 s49, v247, 48
	v_readlane_b32 s38, v168, 0
	v_readlane_b32 s42, v174, 0
	v_readlane_b32 s46, v241, 0
	v_readlane_b32 s50, v247, 0
	v_readlane_b32 s39, v168, 32
	v_readlane_b32 s43, v174, 32
	v_readlane_b32 s47, v241, 32
	v_readlane_b32 s51, v247, 32
	v_mov_b32_e32 v168, s36
	v_mov_b32_e32 v174, s40
	v_mov_b32_e32 v241, s44
	v_mov_b32_e32 v247, s48
	v_mov_b32_e32 v169, s37
	v_mov_b32_e32 v175, s41
	v_mov_b32_e32 v242, s45
	v_mov_b32_e32 v248, s49
	v_add_f32_e32 v168, s38, v168
	v_add_f32_e32 v174, s42, v174
	v_add_f32_e32 v241, s46, v241
	v_add_f32_e32 v247, s50, v247
	v_add_f32_e32 v169, s39, v169
	v_add_f32_e32 v175, s43, v175
	v_add_f32_e32 v242, s47, v242
	v_add_f32_e32 v248, s51, v248
	v_add_f32_e32 v168, v168, v169
	v_add_f32_e32 v174, v174, v175
	v_add_f32_e32 v241, v241, v242
	v_add_f32_e32 v247, v247, v248
	v_fmamk_f32 v100, v168, 0xbc800000, v100
	v_fmamk_f32 v105, v174, 0xbc800000, v105
	v_fmamk_f32 v110, v241, 0xbc800000, v110
	v_fmamk_f32 v115, v247, 0xbc800000, v115
	v_mul_f32_e32 v168, v100, v100
	v_mul_f32_e32 v174, v105, v105
	v_mul_f32_e32 v241, v110, v110
	v_mul_f32_e32 v247, v115, v115
	v_mov_b32_dpp v168, v168 quad_perm:[1,0,3,2] row_mask:0xf bank_mask:0xf bound_ctrl:1
	v_mov_b32_dpp v174, v174 quad_perm:[1,0,3,2] row_mask:0xf bank_mask:0xf bound_ctrl:1
	v_mov_b32_dpp v241, v241 quad_perm:[1,0,3,2] row_mask:0xf bank_mask:0xf bound_ctrl:1
	v_mov_b32_dpp v247, v247 quad_perm:[1,0,3,2] row_mask:0xf bank_mask:0xf bound_ctrl:1
	v_fmac_f32_e32 v168, v100, v100
	v_fmac_f32_e32 v174, v105, v105
	v_fmac_f32_e32 v241, v110, v110
	v_fmac_f32_e32 v247, v115, v115
	v_add_f32_dpp v168, v168, v168 quad_perm:[2,3,0,1] row_mask:0xf bank_mask:0xf bound_ctrl:1
	v_add_f32_dpp v174, v174, v174 quad_perm:[2,3,0,1] row_mask:0xf bank_mask:0xf bound_ctrl:1
	v_add_f32_dpp v241, v241, v241 quad_perm:[2,3,0,1] row_mask:0xf bank_mask:0xf bound_ctrl:1
	v_add_f32_dpp v247, v247, v247 quad_perm:[2,3,0,1] row_mask:0xf bank_mask:0xf bound_ctrl:1
	v_add_f32_dpp v168, v168, v168 row_half_mirror row_mask:0xf bank_mask:0xf bound_ctrl:1
	v_add_f32_dpp v174, v174, v174 row_half_mirror row_mask:0xf bank_mask:0xf bound_ctrl:1
	v_add_f32_dpp v241, v241, v241 row_half_mirror row_mask:0xf bank_mask:0xf bound_ctrl:1
	v_add_f32_dpp v247, v247, v247 row_half_mirror row_mask:0xf bank_mask:0xf bound_ctrl:1
	v_add_f32_dpp v168, v168, v168 row_mirror row_mask:0xf bank_mask:0xf bound_ctrl:1
	v_add_f32_dpp v174, v174, v174 row_mirror row_mask:0xf bank_mask:0xf bound_ctrl:1
	v_add_f32_dpp v241, v241, v241 row_mirror row_mask:0xf bank_mask:0xf bound_ctrl:1
	v_add_f32_dpp v247, v247, v247 row_mirror row_mask:0xf bank_mask:0xf bound_ctrl:1
	v_readlane_b32 s36, v168, 16
	v_readlane_b32 s40, v174, 16
	v_readlane_b32 s44, v241, 16
	v_readlane_b32 s48, v247, 16
	v_readlane_b32 s37, v168, 48
	v_readlane_b32 s41, v174, 48
	v_readlane_b32 s45, v241, 48
	v_readlane_b32 s49, v247, 48
	v_readlane_b32 s38, v168, 0
	v_readlane_b32 s42, v174, 0
	v_readlane_b32 s46, v241, 0
	v_readlane_b32 s50, v247, 0
	v_readlane_b32 s39, v168, 32
	v_readlane_b32 s43, v174, 32
	v_readlane_b32 s47, v241, 32
	v_readlane_b32 s51, v247, 32
	v_mov_b32_e32 v168, s36
	v_mov_b32_e32 v174, s40
	v_mov_b32_e32 v241, s44
	v_mov_b32_e32 v247, s48
	v_mov_b32_e32 v169, s37
	v_mov_b32_e32 v175, s41
	v_mov_b32_e32 v242, s45
	v_mov_b32_e32 v248, s49
	v_add_f32_e32 v168, s38, v168
	v_add_f32_e32 v174, s42, v174
	v_add_f32_e32 v241, s46, v241
	v_add_f32_e32 v247, s50, v247
	v_add_f32_e32 v169, s39, v169
	v_add_f32_e32 v175, s43, v175
	v_add_f32_e32 v242, s47, v242
	v_add_f32_e32 v248, s51, v248
	v_add_f32_e32 v168, v168, v169
	v_add_f32_e32 v174, v174, v175
	v_add_f32_e32 v241, v241, v242
	v_add_f32_e32 v247, v247, v248
	v_fmamk_f32 v168, v168, 0x3c800000, v9
	v_fmamk_f32 v174, v174, 0x3c800000, v9
	v_fmamk_f32 v241, v241, 0x3c800000, v9
; __device__ __forceinline__ float bf2f(bf16 x) { return __uint_as_float(((unsigned)x) << 16); }
; __device__ __forceinline__ unsigned f2bf(float f) { return cvt_pk_bf16(f, 0.f) & 0xffffu; }
; __device__ __forceinline__ void rw_post(Frame& F) {
;     ...
;     for (int u = F.gw; u < 32 * (MR / 64); u += F.NGW) { const int h = u & 31, rb0 = (u >> 5) * 64, col = h * 64 + lane;
;     ...
;                 const float mean = wsum(y[q]) * (1.f / 64.f); const float dv = y[q] - mean; const float var = wsum(dv * dv) * (1.f / 64.f);
;                 const float yn = dv * (1.f / sqrtf(var + 64e-5f)) * g_ + b_;
;                 OB[(size_t)row * DH + col] = (bf16)f2bf((yn + rk[q] * vv[q]) * bf2f(gg[q])); }
	v_fmamk_f32 v247, v247, 0x3c800000, v9
	v_mul_f32_e32 v169, 0x4f800000, v168
	v_mul_f32_e32 v175, 0x4f800000, v174
	v_mul_f32_e32 v242, 0x4f800000, v241
	v_mul_f32_e32 v248, 0x4f800000, v247
	v_cmp_gt_f32_e64 s[52:53], s68, v168
	v_cmp_gt_f32_e64 s[54:55], s68, v174
	v_cmp_gt_f32_e64 s[56:57], s68, v241
	v_cmp_gt_f32_e64 s[58:59], s68, v247
	v_mov_b32_e32 v170, v168
	v_mov_b32_e32 v176, v174
	v_mov_b32_e32 v243, v241
	v_mov_b32_e32 v249, v247
	v_cndmask_b32_e64 v168, v170, v169, s[52:53]
	v_cndmask_b32_e64 v174, v176, v175, s[54:55]
	v_cndmask_b32_e64 v241, v243, v242, s[56:57]
	v_cndmask_b32_e64 v247, v249, v248, s[58:59]
	v_sqrt_f32_e32 v169, v168
	v_sqrt_f32_e32 v175, v174
	v_sqrt_f32_e32 v242, v241
	v_sqrt_f32_e32 v248, v247
	v_add_u32_e32 v170, -1, v169
	v_add_u32_e32 v176, -1, v175
	v_add_u32_e32 v243, -1, v242
	v_add_u32_e32 v249, -1, v248
	v_fma_f32 v171, -v170, v169, v168
	v_fma_f32 v177, -v176, v175, v174
	v_fma_f32 v244, -v243, v242, v241
	v_fma_f32 v250, -v249, v248, v247
	v_cmp_ge_f32_e64 s[60:61], 0, v171
	v_cmp_ge_f32_e64 s[62:63], 0, v177
	v_cmp_ge_f32_e64 s[64:65], 0, v244
	v_cmp_ge_f32_e64 s[66:67], 0, v250
	v_add_u32_e32 v171, 1, v169
	v_add_u32_e32 v177, 1, v175
	v_add_u32_e32 v244, 1, v242
	v_add_u32_e32 v250, 1, v248
	v_cndmask_b32_e64 v170, v169, v170, s[60:61]
	v_cndmask_b32_e64 v176, v175, v176, s[62:63]
	v_cndmask_b32_e64 v243, v242, v243, s[64:65]
	v_cndmask_b32_e64 v249, v248, v249, s[66:67]
	v_fma_f32 v169, -v171, v169, v168
	v_fma_f32 v175, -v177, v175, v174
	v_fma_f32 v242, -v244, v242, v241
	v_fma_f32 v248, -v250, v248, v247
	v_cmp_lt_f32_e64 s[60:61], 0, v169
	v_cmp_lt_f32_e64 s[62:63], 0, v175
	v_cmp_lt_f32_e64 s[64:65], 0, v242
	v_cmp_lt_f32_e64 s[66:67], 0, v248
	v_cndmask_b32_e64 v169, v170, v171, s[60:61]
	v_cndmask_b32_e64 v175, v176, v177, s[62:63]
	v_cndmask_b32_e64 v242, v243, v244, s[64:65]
	v_cndmask_b32_e64 v248, v249, v250, s[66:67]
	v_mul_f32_e32 v170, 0x37800000, v169
	v_mul_f32_e32 v176, 0x37800000, v175
	v_mul_f32_e32 v243, 0x37800000, v242
	v_mul_f32_e32 v249, 0x37800000, v248
	v_cndmask_b32_e64 v169, v169, v170, s[52:53]
	v_cndmask_b32_e64 v175, v175, v176, s[54:55]
	v_cndmask_b32_e64 v242, v242, v243, s[56:57]
	v_cndmask_b32_e64 v248, v248, v249, s[58:59]
	v_cmp_class_f32_e64 s[60:61], v168, v8
	v_cmp_class_f32_e64 s[62:63], v174, v8
	v_cmp_class_f32_e64 s[64:65], v241, v8
	v_cmp_class_f32_e64 s[66:67], v247, v8
	v_cndmask_b32_e64 v168, v169, v168, s[60:61]
	v_cndmask_b32_e64 v174, v175, v174, s[62:63]
	v_cndmask_b32_e64 v241, v242, v241, s[64:65]
	v_cndmask_b32_e64 v247, v248, v247, s[66:67]
	v_div_scale_f32 v169, s[60:61], v168, v168, 1.0
	v_rcp_f32_e32 v170, v169
	s_nop 0
	v_fma_f32 v171, -v169, v170, 1.0
	v_fmac_f32_e32 v170, v171, v170
	v_div_scale_f32 v171, vcc, 1.0, v168, 1.0
	v_mul_f32_e32 v172, v171, v170
	v_fma_f32 v173, -v169, v172, v171
	v_fmac_f32_e32 v172, v173, v170
	v_fma_f32 v169, -v169, v172, v171
	v_div_fmas_f32 v169, v169, v170, v172
	v_div_fixup_f32 v168, v169, v168, 1.0
	v_div_scale_f32 v175, s[62:63], v174, v174, 1.0
	v_rcp_f32_e32 v176, v175
	s_nop 0
	v_fma_f32 v177, -v175, v176, 1.0
	v_fmac_f32_e32 v176, v177, v176
	v_div_scale_f32 v177, vcc, 1.0, v174, 1.0
	v_mul_f32_e32 v236, v177, v176
	v_fma_f32 v237, -v175, v236, v177
	v_fmac_f32_e32 v236, v237, v176
	v_fma_f32 v175, -v175, v236, v177
	v_div_fmas_f32 v175, v175, v176, v236
	v_div_fixup_f32 v174, v175, v174, 1.0
	v_div_scale_f32 v242, s[64:65], v241, v241, 1.0
	v_rcp_f32_e32 v243, v242
	s_nop 0
	v_fma_f32 v244, -v242, v243, 1.0
	v_fmac_f32_e32 v243, v244, v243
	v_div_scale_f32 v244, vcc, 1.0, v241, 1.0
	v_mul_f32_e32 v245, v244, v243
	v_fma_f32 v246, -v242, v245, v244
	v_fmac_f32_e32 v245, v246, v243
	v_fma_f32 v242, -v242, v245, v244
	v_div_fmas_f32 v242, v242, v243, v245
	v_div_fixup_f32 v241, v242, v241, 1.0
	v_div_scale_f32 v248, s[66:67], v247, v247, 1.0
	v_rcp_f32_e32 v249, v248
	s_nop 0
	v_fma_f32 v250, -v248, v249, 1.0
	v_fmac_f32_e32 v249, v250, v249
	v_div_scale_f32 v250, vcc, 1.0, v247, 1.0
	v_mul_f32_e32 v251, v250, v249
	v_fma_f32 v252, -v248, v251, v250
	v_fmac_f32_e32 v251, v252, v249
	v_fma_f32 v248, -v248, v251, v250
	v_div_fmas_f32 v248, v248, v249, v251
	v_div_fixup_f32 v247, v248, v247, 1.0
	v_mul_f32_e32 v100, v100, v168
	v_mul_f32_e32 v105, v105, v174
	v_mul_f32_e32 v110, v110, v241
	v_mul_f32_e32 v115, v115, v247
	v_lshlrev_b32_e32 v103, 16, v103
	v_lshlrev_b32_e32 v108, 16, v108
	v_lshlrev_b32_e32 v113, 16, v113
	v_lshlrev_b32_e32 v118, 16, v118
	v_fma_f32 v100, v6, v100, v7
	v_fma_f32 v105, v6, v105, v7
	v_fma_f32 v110, v6, v110, v7
	v_fma_f32 v115, v6, v115, v7
	v_fmac_f32_e32 v100, s73, v101
	v_fmac_f32_e32 v105, s26, v106
	v_fmac_f32_e32 v110, s27, v111
	v_fmac_f32_e32 v115, s32, v116
	v_mul_f32_e32 v100, v100, v103
	v_mul_f32_e32 v105, v105, v108
	v_mul_f32_e32 v110, v110, v113
	v_mul_f32_e32 v115, v115, v118
	v_cvt_pk_bf16_f32 v169, v100, v100
	v_cvt_pk_bf16_f32 v175, v105, v105
	v_cvt_pk_bf16_f32 v242, v110, v110
	v_cvt_pk_bf16_f32 v248, v115, v115
	global_store_short v2, v169, s[28:29]
	s_add_u32 s28, s28, 0x1000
	s_addc_u32 s29, s29, 0
	global_store_short v2, v175, s[28:29]
	s_add_u32 s28, s28, 0x1000
	s_addc_u32 s29, s29, 0
	global_store_short v2, v242, s[28:29]
	s_add_u32 s28, s28, 0x1000
	s_addc_u32 s29, s29, 0
	global_store_short v2, v248, s[28:29]
	s_add_u32 s28, s28, 0x1000
	s_addc_u32 s29, s29, 0
	s_sub_u32 s25, s25, 1
	s_cmp_lg_u32 s25, 0
	s_cbranch_scc1 .Lpo_pair
	s_add_i32 s20, s20, s92
	s_cmpk_lt_i32 s20, 0x2040
	s_cbranch_scc1 .Lpo_unit
